# as previous but 6 (instead of 4) MFMAs of each compute segment issue before the segment barrier
# baseline (speedup 1.0000x reference)
; #define PG8_STAGE(bufoff, gbase, voff) do { _Pragma("unroll") for (int _i = 0; _i < 2; ++_i) \
;         __builtin_amdgcn_global_load_lds((const unsigned*)((const char*)(gbase) + (voff)[_i]), (PG8_LAS unsigned*)(lds + (bufoff) + ldsw + _i * 8192), 16, 0, 0); } while (0)
; #define PG8_LDA(dst, b, h) do { _Pragma("unroll") for (int m = 0; m < 4; ++m) _Pragma("unroll") for (int k = 0; k < 2; ++k) dst[m][k] = *(const PG8_LAS bf16x8*)(lds + PG8_SA(b, h) + aoff + m * 2048 + k * 1024); } while (0)
; #define PG8_LDB(dst, b, h) do { _Pragma("unroll") for (int n = 0; n < 2; ++n) _Pragma("unroll") for (int k = 0; k < 2; ++k) dst[n][k] = *(const PG8_LAS bf16x8*)(lds + PG8_SB(b, h) + boff + n * 2048 + k * 1024); } while (0)
; #define PG8_MMA(ai, bj, At, Bt) do { __builtin_amdgcn_s_setprio(1); _Pragma("unroll") for (int m = 0; m < 4; ++m) _Pragma("unroll") for (int n = 0; n < 2; ++n) _Pragma("unroll") for (int k = 0; k < 2; ++k) \
;         acc[ai][bj][m][n] = __builtin_amdgcn_mfma_f32_16x16x32_bf16(Bt[n][k], At[m][k], acc[ai][bj][m][n], 0, 0, 0); __builtin_amdgcn_s_setprio(0); } while (0)
; #define PG8_WAIT_V(n) asm volatile("s_waitcnt vmcnt(" #n ")" ::: "memory")
; #define PG8_WAIT_L(n) asm volatile("s_waitcnt lgkmcnt(" #n ")" ::: "memory")
; #define PG8_BAR __builtin_amdgcn_s_barrier()
; #define PG8_SCHED __builtin_amdgcn_sched_barrier(0)
; template <class Epi, class Sched, bool ALIGN_EPI = false, bool SP2 = false, bool ABLK = false, bool BBLK = false>
; __device__ __forceinline__ void gemm_phase(PG8_LAS unsigned char* lds, const Gemm g, const Sched& S, const Epi& E) {
;     ...
;             PG8_LDB(B0, 0, 0); PG8_LDB(B1, 0, 1); PG8_SCHED; PG8_LDA(At, 0, 0); PG8_STAGE(PG8_SA(1, 1), a1 + hstepA, voffA);
;             PG8_WAIT_V(8); PG8_WAIT_L(0); PG8_BAR; PG8_MMA(0, 0, At, B0); PG8_MMA(0, 1, At, B1); PG8_BAR; PG8_SCHED;
;             PG8_LDA(At, 0, 1); PG8_STAGE(PG8_SB(0, 0), b2, voffB); PG8_STAGE(PG8_SB(0, 1), b2 + hstepB, voffB); PG8_STAGE(PG8_SA(0, 0), a2, voffA);
;             PG8_WAIT_V(8); PG8_WAIT_L(0); PG8_BAR; PG8_MMA(1, 0, At, B0); PG8_MMA(1, 1, At, B1); PG8_BAR; PG8_SCHED;
.LBB0_185:
	s_add_u32 s13, s20, 0x4000
	s_addc_u32 s22, s21, 0
	s_cmp_eq_u32 vcc_hi, 28
	s_cselect_b32 s26, s70, s13
	s_cselect_b32 s27, s9, s22
	s_cselect_b32 s24, s71, s77
	s_cselect_b32 s25, s7, vcc_lo
	s_add_u32 s22, s26, 0x8000
	s_addc_u32 s23, s27, 0
	s_add_i32 s13, 0, 0x10000
	v_add_u32_e32 v36, s13, v160
	s_add_i32 s88, 0, 0x14000
	ds_read_b128 v[152:155], v36
	ds_read_b128 v[156:159], v36 offset:1024
	ds_read_b128 v[162:165], v36 offset:2048
	ds_read_b128 v[166:169], v36 offset:3072
	v_add_u32_e32 v36, s88, v160
	ds_read_b128 v[170:173], v36
	ds_read_b128 v[174:177], v36 offset:1024
	ds_read_b128 v[178:181], v36 offset:2048
	ds_read_b128 v[182:185], v36 offset:3072
	s_add_i32 m0, s19, 0xc000
	ds_read_b128 v[186:189], v161
	ds_read_b128 v[190:193], v161 offset:1024
	ds_read_b128 v[194:197], v161 offset:2048
	ds_read_b128 v[198:201], v161 offset:3072
	ds_read_b128 v[202:205], v161 offset:4096
	ds_read_b128 v[206:209], v161 offset:5120
	ds_read_b128 v[210:213], v161 offset:6144
	ds_read_b128 v[214:217], v161 offset:7168
	global_load_lds_dwordx4 v148, s[20:21]
	s_add_i32 m0, s19, 0xe000
	s_nop 0
	global_load_lds_dwordx4 v150, s[20:21]
	s_waitcnt vmcnt(8)
	s_waitcnt lgkmcnt(0)
	v_mfma_f32_16x16x32_bf16 v[132:135], v[152:155], v[186:189], v[132:135]
	v_mfma_f32_16x16x32_bf16 v[128:131], v[162:165], v[186:189], v[128:131]
	v_mfma_f32_16x16x32_bf16 v[116:119], v[152:155], v[194:197], v[116:119]
	v_mfma_f32_16x16x32_bf16 v[112:115], v[162:165], v[194:197], v[112:115]
	v_mfma_f32_16x16x32_bf16 v[100:103], v[152:155], v[202:205], v[100:103]
	v_mfma_f32_16x16x32_bf16 v[96:99], v[162:165], v[202:205], v[96:99]
	s_barrier
	s_setprio 1
	v_mfma_f32_16x16x32_bf16 v[84:87], v[152:155], v[210:213], v[84:87]
	v_mfma_f32_16x16x32_bf16 v[80:83], v[162:165], v[210:213], v[80:83]
	v_mfma_f32_16x16x32_bf16 v[132:135], v[156:159], v[190:193], v[132:135]
	v_mfma_f32_16x16x32_bf16 v[128:131], v[166:169], v[190:193], v[128:131]
	v_mfma_f32_16x16x32_bf16 v[116:119], v[156:159], v[198:201], v[116:119]
	v_mfma_f32_16x16x32_bf16 v[112:115], v[166:169], v[198:201], v[112:115]
	v_mfma_f32_16x16x32_bf16 v[100:103], v[156:159], v[206:209], v[100:103]
	v_mfma_f32_16x16x32_bf16 v[96:99], v[166:169], v[206:209], v[96:99]
	v_mfma_f32_16x16x32_bf16 v[84:87], v[156:159], v[214:217], v[84:87]
	v_mfma_f32_16x16x32_bf16 v[80:83], v[166:169], v[214:217], v[80:83]
	s_setprio 0
	s_setprio 1
	v_mfma_f32_16x16x32_bf16 v[124:127], v[170:173], v[186:189], v[124:127]
	v_mfma_f32_16x16x32_bf16 v[120:123], v[178:181], v[186:189], v[120:123]
	v_mfma_f32_16x16x32_bf16 v[108:111], v[170:173], v[194:197], v[108:111]
	v_mfma_f32_16x16x32_bf16 v[104:107], v[178:181], v[194:197], v[104:107]
	v_mfma_f32_16x16x32_bf16 v[92:95], v[170:173], v[202:205], v[92:95]
	v_mfma_f32_16x16x32_bf16 v[88:91], v[178:181], v[202:205], v[88:91]
	v_mfma_f32_16x16x32_bf16 v[76:79], v[170:173], v[210:213], v[76:79]
	v_mfma_f32_16x16x32_bf16 v[72:75], v[178:181], v[210:213], v[72:75]
	v_mfma_f32_16x16x32_bf16 v[124:127], v[174:177], v[190:193], v[124:127]
	v_mfma_f32_16x16x32_bf16 v[120:123], v[182:185], v[190:193], v[120:123]
	v_mfma_f32_16x16x32_bf16 v[108:111], v[174:177], v[198:201], v[108:111]
	v_mfma_f32_16x16x32_bf16 v[104:107], v[182:185], v[198:201], v[104:107]
	v_mfma_f32_16x16x32_bf16 v[92:95], v[174:177], v[206:209], v[92:95]
	v_mfma_f32_16x16x32_bf16 v[88:91], v[182:185], v[206:209], v[88:91]
	v_mfma_f32_16x16x32_bf16 v[76:79], v[174:177], v[214:217], v[76:79]
	v_mfma_f32_16x16x32_bf16 v[72:75], v[182:185], v[214:217], v[72:75]
	s_setprio 0
	s_barrier
	s_add_i32 s13, s13, s31
	s_mov_b32 m0, s13
	ds_read_b128 v[186:189], v161 offset:16384
	ds_read_b128 v[190:193], v161 offset:17408
	ds_read_b128 v[194:197], v161 offset:18432
	ds_read_b128 v[198:201], v161 offset:19456
	ds_read_b128 v[202:205], v161 offset:20480
	ds_read_b128 v[206:209], v161 offset:21504
	ds_read_b128 v[210:213], v161 offset:22528
	ds_read_b128 v[214:217], v161 offset:23552
	global_load_lds_dwordx4 v140, s[24:25]
	s_add_i32 m0, s13, 0x2000
	s_add_u32 s68, s24, 0x4000
	s_addc_u32 s69, s25, 0
	s_add_i32 s13, s88, s31
	global_load_lds_dwordx4 v136, s[24:25]
	s_mov_b32 m0, s13
	s_nop 0
	global_load_lds_dwordx4 v140, s[68:69]
	s_add_i32 m0, s13, 0x2000
	s_nop 0
	global_load_lds_dwordx4 v136, s[68:69]
	s_mov_b32 m0, s19
	s_nop 0
	global_load_lds_dwordx4 v142, s[26:27]
	s_mov_b32 m0, s35
	s_nop 0
	global_load_lds_dwordx4 v138, s[26:27]
	s_waitcnt vmcnt(8)
	s_waitcnt lgkmcnt(0)
	v_mfma_f32_16x16x32_bf16 v[68:71], v[152:155], v[186:189], v[68:71]
	v_mfma_f32_16x16x32_bf16 v[64:67], v[162:165], v[186:189], v[64:67]
	v_mfma_f32_16x16x32_bf16 v[52:55], v[152:155], v[194:197], v[52:55]
	v_mfma_f32_16x16x32_bf16 v[48:51], v[162:165], v[194:197], v[48:51]
	v_mfma_f32_16x16x32_bf16 v[32:35], v[152:155], v[202:205], v[32:35]
	v_mfma_f32_16x16x32_bf16 v[28:31], v[162:165], v[202:205], v[28:31]
	s_barrier
; #define PG8_STAGE(bufoff, gbase, voff) do { _Pragma("unroll") for (int _i = 0; _i < 2; ++_i) \
;         __builtin_amdgcn_global_load_lds((const unsigned*)((const char*)(gbase) + (voff)[_i]), (PG8_LAS unsigned*)(lds + (bufoff) + ldsw + _i * 8192), 16, 0, 0); } while (0)
; #define PG8_LDA(dst, b, h) do { _Pragma("unroll") for (int m = 0; m < 4; ++m) _Pragma("unroll") for (int k = 0; k < 2; ++k) dst[m][k] = *(const PG8_LAS bf16x8*)(lds + PG8_SA(b, h) + aoff + m * 2048 + k * 1024); } while (0)
; #define PG8_LDB(dst, b, h) do { _Pragma("unroll") for (int n = 0; n < 2; ++n) _Pragma("unroll") for (int k = 0; k < 2; ++k) dst[n][k] = *(const PG8_LAS bf16x8*)(lds + PG8_SB(b, h) + boff + n * 2048 + k * 1024); } while (0)
; #define PG8_MMA(ai, bj, At, Bt) do { __builtin_amdgcn_s_setprio(1); _Pragma("unroll") for (int m = 0; m < 4; ++m) _Pragma("unroll") for (int n = 0; n < 2; ++n) _Pragma("unroll") for (int k = 0; k < 2; ++k) \
;         acc[ai][bj][m][n] = __builtin_amdgcn_mfma_f32_16x16x32_bf16(Bt[n][k], At[m][k], acc[ai][bj][m][n], 0, 0, 0); __builtin_amdgcn_s_setprio(0); } while (0)
; #define PG8_WAIT_V(n) asm volatile("s_waitcnt vmcnt(" #n ")" ::: "memory")
; #define PG8_WAIT_L(n) asm volatile("s_waitcnt lgkmcnt(" #n ")" ::: "memory")
; #define PG8_BAR __builtin_amdgcn_s_barrier()
; #define PG8_SCHED __builtin_amdgcn_sched_barrier(0)
; template <class Epi, class Sched, bool ALIGN_EPI = false, bool SP2 = false, bool ABLK = false, bool BBLK = false>
; __device__ __forceinline__ void gemm_phase(PG8_LAS unsigned char* lds, const Gemm g, const Sched& S, const Epi& E) {
;     ...
;             PG8_WAIT_V(8); PG8_WAIT_L(0); PG8_BAR; PG8_MMA(1, 0, At, B0); PG8_MMA(1, 1, At, B1); PG8_BAR; PG8_SCHED;
;             PG8_LDB(B0, 1, 0); PG8_LDB(B1, 1, 1); PG8_SCHED; PG8_LDA(At, 1, 0); PG8_STAGE(PG8_SA(0, 1), a2 + hstepA, voffA);
;             PG8_WAIT_V(8); PG8_WAIT_L(0); PG8_BAR; PG8_MMA(0, 0, At, B0); PG8_MMA(0, 1, At, B1); PG8_BAR; PG8_SCHED;
	s_setprio 1
	v_mfma_f32_16x16x32_bf16 v[16:19], v[152:155], v[210:213], v[16:19]
	v_mfma_f32_16x16x32_bf16 v[12:15], v[162:165], v[210:213], v[12:15]
	v_mfma_f32_16x16x32_bf16 v[68:71], v[156:159], v[190:193], v[68:71]
	v_mfma_f32_16x16x32_bf16 v[64:67], v[166:169], v[190:193], v[64:67]
	v_mfma_f32_16x16x32_bf16 v[52:55], v[156:159], v[198:201], v[52:55]
	v_mfma_f32_16x16x32_bf16 v[48:51], v[166:169], v[198:201], v[48:51]
	v_mfma_f32_16x16x32_bf16 v[32:35], v[156:159], v[206:209], v[32:35]
	v_mfma_f32_16x16x32_bf16 v[28:31], v[166:169], v[206:209], v[28:31]
	v_mfma_f32_16x16x32_bf16 v[16:19], v[156:159], v[214:217], v[16:19]
	v_mfma_f32_16x16x32_bf16 v[12:15], v[166:169], v[214:217], v[12:15]
	s_setprio 0
	s_setprio 1
	v_mfma_f32_16x16x32_bf16 v[60:63], v[170:173], v[186:189], v[60:63]
	v_mfma_f32_16x16x32_bf16 v[56:59], v[178:181], v[186:189], v[56:59]
	v_mfma_f32_16x16x32_bf16 v[44:47], v[170:173], v[194:197], v[44:47]
	v_mfma_f32_16x16x32_bf16 v[40:43], v[178:181], v[194:197], v[40:43]
	v_mfma_f32_16x16x32_bf16 v[24:27], v[170:173], v[202:205], v[24:27]
	v_mfma_f32_16x16x32_bf16 v[20:23], v[178:181], v[202:205], v[20:23]
	v_mfma_f32_16x16x32_bf16 v[8:11], v[170:173], v[210:213], v[8:11]
	v_mfma_f32_16x16x32_bf16 v[4:7], v[178:181], v[210:213], v[4:7]
	v_mfma_f32_16x16x32_bf16 v[60:63], v[174:177], v[190:193], v[60:63]
	v_mfma_f32_16x16x32_bf16 v[56:59], v[182:185], v[190:193], v[56:59]
	v_mfma_f32_16x16x32_bf16 v[44:47], v[174:177], v[198:201], v[44:47]
	v_mfma_f32_16x16x32_bf16 v[40:43], v[182:185], v[198:201], v[40:43]
	v_mfma_f32_16x16x32_bf16 v[24:27], v[174:177], v[206:209], v[24:27]
	v_mfma_f32_16x16x32_bf16 v[20:23], v[182:185], v[206:209], v[20:23]
	v_mfma_f32_16x16x32_bf16 v[8:11], v[174:177], v[214:217], v[8:11]
	v_mfma_f32_16x16x32_bf16 v[4:7], v[182:185], v[214:217], v[4:7]
	s_setprio 0
	s_barrier
	s_add_i32 s13, 0, 0x18000
	v_add_u32_e32 v36, s13, v160
	s_add_i32 s68, 0, 0x1c000
	ds_read_b128 v[152:155], v36
	ds_read_b128 v[156:159], v36 offset:1024
	ds_read_b128 v[162:165], v36 offset:2048
	ds_read_b128 v[166:169], v36 offset:3072
	v_add_u32_e32 v36, s68, v160
	ds_read_b128 v[170:173], v36
	ds_read_b128 v[174:177], v36 offset:1024
	ds_read_b128 v[178:181], v36 offset:2048
	ds_read_b128 v[182:185], v36 offset:3072
	s_add_u32 s26, s26, 0x4000
	s_addc_u32 s27, s27, 0
	s_mov_b32 m0, s36
	ds_read_b128 v[186:189], v161 offset:32768
	ds_read_b128 v[190:193], v161 offset:33792
	ds_read_b128 v[194:197], v161 offset:34816
	ds_read_b128 v[198:201], v161 offset:35840
	ds_read_b128 v[202:205], v161 offset:36864
	ds_read_b128 v[206:209], v161 offset:37888
	ds_read_b128 v[210:213], v161 offset:38912
	ds_read_b128 v[214:217], v161 offset:39936
	global_load_lds_dwordx4 v142, s[26:27]
	s_mov_b32 m0, s37
	s_nop 0
	global_load_lds_dwordx4 v138, s[26:27]
	s_waitcnt vmcnt(8)
	s_waitcnt lgkmcnt(0)
	v_mfma_f32_16x16x32_bf16 v[132:135], v[152:155], v[186:189], v[132:135]
	v_mfma_f32_16x16x32_bf16 v[128:131], v[162:165], v[186:189], v[128:131]
	v_mfma_f32_16x16x32_bf16 v[116:119], v[152:155], v[194:197], v[116:119]
	v_mfma_f32_16x16x32_bf16 v[112:115], v[162:165], v[194:197], v[112:115]
	v_mfma_f32_16x16x32_bf16 v[100:103], v[152:155], v[202:205], v[100:103]
	v_mfma_f32_16x16x32_bf16 v[96:99], v[162:165], v[202:205], v[96:99]
	s_barrier
	s_setprio 1
	v_mfma_f32_16x16x32_bf16 v[84:87], v[152:155], v[210:213], v[84:87]
	v_mfma_f32_16x16x32_bf16 v[80:83], v[162:165], v[210:213], v[80:83]
	v_mfma_f32_16x16x32_bf16 v[132:135], v[156:159], v[190:193], v[132:135]
	v_mfma_f32_16x16x32_bf16 v[128:131], v[166:169], v[190:193], v[128:131]
	v_mfma_f32_16x16x32_bf16 v[116:119], v[156:159], v[198:201], v[116:119]
	v_mfma_f32_16x16x32_bf16 v[112:115], v[166:169], v[198:201], v[112:115]
	v_mfma_f32_16x16x32_bf16 v[100:103], v[156:159], v[206:209], v[100:103]
	v_mfma_f32_16x16x32_bf16 v[96:99], v[166:169], v[206:209], v[96:99]
	v_mfma_f32_16x16x32_bf16 v[84:87], v[156:159], v[214:217], v[84:87]
	v_mfma_f32_16x16x32_bf16 v[80:83], v[166:169], v[214:217], v[80:83]
	s_setprio 0
	s_setprio 1
	v_mfma_f32_16x16x32_bf16 v[124:127], v[170:173], v[186:189], v[124:127]
	v_mfma_f32_16x16x32_bf16 v[120:123], v[178:181], v[186:189], v[120:123]
	v_mfma_f32_16x16x32_bf16 v[108:111], v[170:173], v[194:197], v[108:111]
	v_mfma_f32_16x16x32_bf16 v[104:107], v[178:181], v[194:197], v[104:107]
	v_mfma_f32_16x16x32_bf16 v[92:95], v[170:173], v[202:205], v[92:95]
	v_mfma_f32_16x16x32_bf16 v[88:91], v[178:181], v[202:205], v[88:91]
	v_mfma_f32_16x16x32_bf16 v[76:79], v[170:173], v[210:213], v[76:79]
	v_mfma_f32_16x16x32_bf16 v[72:75], v[178:181], v[210:213], v[72:75]
	v_mfma_f32_16x16x32_bf16 v[124:127], v[174:177], v[190:193], v[124:127]
	v_mfma_f32_16x16x32_bf16 v[120:123], v[182:185], v[190:193], v[120:123]
	v_mfma_f32_16x16x32_bf16 v[108:111], v[174:177], v[198:201], v[108:111]
	v_mfma_f32_16x16x32_bf16 v[104:107], v[182:185], v[198:201], v[104:107]
	v_mfma_f32_16x16x32_bf16 v[92:95], v[174:177], v[206:209], v[92:95]
	v_mfma_f32_16x16x32_bf16 v[88:91], v[182:185], v[206:209], v[88:91]
	v_mfma_f32_16x16x32_bf16 v[76:79], v[174:177], v[214:217], v[76:79]
	v_mfma_f32_16x16x32_bf16 v[72:75], v[182:185], v[214:217], v[72:75]
	s_setprio 0
	s_barrier
; #define PG8_STAGE(bufoff, gbase, voff) do { _Pragma("unroll") for (int _i = 0; _i < 2; ++_i) \
;         __builtin_amdgcn_global_load_lds((const unsigned*)((const char*)(gbase) + (voff)[_i]), (PG8_LAS unsigned*)(lds + (bufoff) + ldsw + _i * 8192), 16, 0, 0); } while (0)
; #define PG8_LDA(dst, b, h) do { _Pragma("unroll") for (int m = 0; m < 4; ++m) _Pragma("unroll") for (int k = 0; k < 2; ++k) dst[m][k] = *(const PG8_LAS bf16x8*)(lds + PG8_SA(b, h) + aoff + m * 2048 + k * 1024); } while (0)
; #define PG8_MMA(ai, bj, At, Bt) do { __builtin_amdgcn_s_setprio(1); _Pragma("unroll") for (int m = 0; m < 4; ++m) _Pragma("unroll") for (int n = 0; n < 2; ++n) _Pragma("unroll") for (int k = 0; k < 2; ++k) \
;         acc[ai][bj][m][n] = __builtin_amdgcn_mfma_f32_16x16x32_bf16(Bt[n][k], At[m][k], acc[ai][bj][m][n], 0, 0, 0); __builtin_amdgcn_s_setprio(0); } while (0)
; #define PG8_WAIT_V(n) asm volatile("s_waitcnt vmcnt(" #n ")" ::: "memory")
; #define PG8_WAIT_L(n) asm volatile("s_waitcnt lgkmcnt(" #n ")" ::: "memory")
; #define PG8_BAR __builtin_amdgcn_s_barrier()
; #define PG8_SCHED __builtin_amdgcn_sched_barrier(0)
; template <class Epi, class Sched, bool ALIGN_EPI = false, bool SP2 = false, bool ABLK = false, bool BBLK = false>
; __device__ __forceinline__ void gemm_phase(PG8_LAS unsigned char* lds, const Gemm g, const Sched& S, const Epi& E) {
;     ...
;             PG8_LDA(At, 1, 1); PG8_STAGE(PG8_SB(1, 0), b3, voffB); PG8_STAGE(PG8_SB(1, 1), b3 + hstepB, voffB); PG8_STAGE(PG8_SA(1, 0), a3, voffA);
;             PG8_WAIT_V(8); PG8_WAIT_L(0); PG8_BAR; PG8_MMA(1, 0, At, B0); PG8_MMA(1, 1, At, B1); PG8_BAR; PG8_SCHED;
;     ...
;         if constexpr (ALIGN_EPI) { if (wr == 0) PG8_BAR; }
;         if constexpr (!Epi::AFTER_DRAIN) { E(acc, cur, wr, wc, fr, fq, rs_area); S.done(cur); }
	s_add_u32 s26, s24, 0x8000
	s_addc_u32 s27, s25, 0
	s_add_i32 s13, s13, s31
	s_mov_b32 m0, s13
	ds_read_b128 v[186:189], v161 offset:49152
	ds_read_b128 v[190:193], v161 offset:50176
	ds_read_b128 v[194:197], v161 offset:51200
	ds_read_b128 v[198:201], v161 offset:52224
	ds_read_b128 v[202:205], v161 offset:53248
	ds_read_b128 v[206:209], v161 offset:54272
	ds_read_b128 v[210:213], v161 offset:55296
	ds_read_b128 v[214:217], v161 offset:56320
	global_load_lds_dwordx4 v140, s[26:27]
	s_add_i32 m0, s13, 0x2000
	s_add_u32 s24, s24, 0xc000
	s_addc_u32 s25, s25, 0
	s_add_i32 s13, s68, s31
	global_load_lds_dwordx4 v136, s[26:27]
	s_mov_b32 m0, s13
	s_nop 0
	global_load_lds_dwordx4 v140, s[24:25]
	s_add_i32 m0, s13, 0x2000
	s_nop 0
	global_load_lds_dwordx4 v136, s[24:25]
	s_mov_b32 m0, s62
	s_nop 0
	global_load_lds_dwordx4 v142, s[22:23]
	s_mov_b32 m0, s63
	s_nop 0
	global_load_lds_dwordx4 v138, s[22:23]
	s_waitcnt vmcnt(8)
	s_waitcnt lgkmcnt(0)
	v_mfma_f32_16x16x32_bf16 v[68:71], v[152:155], v[186:189], v[68:71]
	v_mfma_f32_16x16x32_bf16 v[64:67], v[162:165], v[186:189], v[64:67]
	v_mfma_f32_16x16x32_bf16 v[52:55], v[152:155], v[194:197], v[52:55]
	v_mfma_f32_16x16x32_bf16 v[48:51], v[162:165], v[194:197], v[48:51]
	v_mfma_f32_16x16x32_bf16 v[32:35], v[152:155], v[202:205], v[32:35]
	v_mfma_f32_16x16x32_bf16 v[28:31], v[162:165], v[202:205], v[28:31]
	s_barrier
	s_setprio 1
	v_mfma_f32_16x16x32_bf16 v[16:19], v[152:155], v[210:213], v[16:19]
	v_mfma_f32_16x16x32_bf16 v[12:15], v[162:165], v[210:213], v[12:15]
	v_mfma_f32_16x16x32_bf16 v[68:71], v[156:159], v[190:193], v[68:71]
	v_mfma_f32_16x16x32_bf16 v[64:67], v[166:169], v[190:193], v[64:67]
	v_mfma_f32_16x16x32_bf16 v[52:55], v[156:159], v[198:201], v[52:55]
	v_mfma_f32_16x16x32_bf16 v[48:51], v[166:169], v[198:201], v[48:51]
	v_mfma_f32_16x16x32_bf16 v[32:35], v[156:159], v[206:209], v[32:35]
	v_mfma_f32_16x16x32_bf16 v[28:31], v[166:169], v[206:209], v[28:31]
	v_mfma_f32_16x16x32_bf16 v[16:19], v[156:159], v[214:217], v[16:19]
	v_mfma_f32_16x16x32_bf16 v[12:15], v[166:169], v[214:217], v[12:15]
	s_setprio 0
	s_setprio 1
	v_mfma_f32_16x16x32_bf16 v[60:63], v[170:173], v[186:189], v[60:63]
	v_mfma_f32_16x16x32_bf16 v[56:59], v[178:181], v[186:189], v[56:59]
	v_mfma_f32_16x16x32_bf16 v[44:47], v[170:173], v[194:197], v[44:47]
	v_mfma_f32_16x16x32_bf16 v[40:43], v[178:181], v[194:197], v[40:43]
	v_mfma_f32_16x16x32_bf16 v[24:27], v[170:173], v[202:205], v[24:27]
	v_mfma_f32_16x16x32_bf16 v[20:23], v[178:181], v[202:205], v[20:23]
	v_mfma_f32_16x16x32_bf16 v[8:11], v[170:173], v[210:213], v[8:11]
	v_mfma_f32_16x16x32_bf16 v[4:7], v[178:181], v[210:213], v[4:7]
	v_mfma_f32_16x16x32_bf16 v[60:63], v[174:177], v[190:193], v[60:63]
	v_mfma_f32_16x16x32_bf16 v[56:59], v[182:185], v[190:193], v[56:59]
	v_mfma_f32_16x16x32_bf16 v[44:47], v[174:177], v[198:201], v[44:47]
	v_mfma_f32_16x16x32_bf16 v[40:43], v[182:185], v[198:201], v[40:43]
	v_mfma_f32_16x16x32_bf16 v[24:27], v[174:177], v[206:209], v[24:27]
	v_mfma_f32_16x16x32_bf16 v[20:23], v[182:185], v[206:209], v[20:23]
	v_mfma_f32_16x16x32_bf16 v[8:11], v[174:177], v[214:217], v[8:11]
	v_mfma_f32_16x16x32_bf16 v[4:7], v[182:185], v[214:217], v[4:7]
	s_setprio 0
	s_barrier
	s_add_i32 vcc_hi, vcc_hi, 2
	s_add_u32 s20, s20, 0x10000
	s_addc_u32 s21, s21, 0
	s_add_u32 s77, s77, 0x10000
	s_addc_u32 vcc_lo, vcc_lo, 0
	s_cmp_gt_u32 vcc_hi, 29
	s_cbranch_scc0 .LBB0_185
	s_and_b64 vcc, exec, s[4:5]
	s_cbranch_vccz .LBB0_188
	s_barrier

; #define PG8_STAGE(bufoff, gbase, voff) do { _Pragma("unroll") for (int _i = 0; _i < 2; ++_i) \
;         __builtin_amdgcn_global_load_lds((const unsigned*)((const char*)(gbase) + (voff)[_i]), (PG8_LAS unsigned*)(lds + (bufoff) + ldsw + _i * 8192), 16, 0, 0); } while (0)
; #define PG8_LDA(dst, b, h) do { _Pragma("unroll") for (int m = 0; m < 4; ++m) _Pragma("unroll") for (int k = 0; k < 2; ++k) dst[m][k] = *(const PG8_LAS bf16x8*)(lds + PG8_SA(b, h) + aoff + m * 2048 + k * 1024); } while (0)
; #define PG8_LDB(dst, b, h) do { _Pragma("unroll") for (int n = 0; n < 2; ++n) _Pragma("unroll") for (int k = 0; k < 2; ++k) dst[n][k] = *(const PG8_LAS bf16x8*)(lds + PG8_SB(b, h) + boff + n * 2048 + k * 1024); } while (0)
; #define PG8_MMA(ai, bj, At, Bt) do { __builtin_amdgcn_s_setprio(1); _Pragma("unroll") for (int m = 0; m < 4; ++m) _Pragma("unroll") for (int n = 0; n < 2; ++n) _Pragma("unroll") for (int k = 0; k < 2; ++k) \
;         acc[ai][bj][m][n] = __builtin_amdgcn_mfma_f32_16x16x32_bf16(Bt[n][k], At[m][k], acc[ai][bj][m][n], 0, 0, 0); __builtin_amdgcn_s_setprio(0); } while (0)
; #define PG8_WAIT_V(n) asm volatile("s_waitcnt vmcnt(" #n ")" ::: "memory")
; #define PG8_WAIT_L(n) asm volatile("s_waitcnt lgkmcnt(" #n ")" ::: "memory")
; #define PG8_BAR __builtin_amdgcn_s_barrier()
; #define PG8_SCHED __builtin_amdgcn_sched_barrier(0)
; template <class Epi, class Sched, bool ALIGN_EPI = false, bool SP2 = false, bool ABLK = false, bool BBLK = false>
; __device__ __forceinline__ void gemm_phase(PG8_LAS unsigned char* lds, const Gemm g, const Sched& S, const Epi& E) {
;     ...
;             PG8_LDB(B0, 0, 0); PG8_LDB(B1, 0, 1); PG8_SCHED; PG8_LDA(At, 0, 0); PG8_STAGE(PG8_SA(1, 1), a1 + hstepA, voffA);
;             PG8_WAIT_V(8); PG8_WAIT_L(0); PG8_BAR; PG8_MMA(0, 0, At, B0); PG8_MMA(0, 1, At, B1); PG8_BAR; PG8_SCHED;
;             PG8_LDA(At, 0, 1); PG8_STAGE(PG8_SB(0, 0), b2, voffB); PG8_STAGE(PG8_SB(0, 1), b2 + hstepB, voffB); PG8_STAGE(PG8_SA(0, 0), a2, voffA);
;             PG8_WAIT_V(8); PG8_WAIT_L(0); PG8_BAR; PG8_MMA(1, 0, At, B0); PG8_MMA(1, 1, At, B1); PG8_BAR; PG8_SCHED;
.LBB0_439:
	s_add_u32 s16, s10, 0x4000
	s_addc_u32 s17, s11, 0
	s_cmpk_eq_i32 s13, 0x54
	s_cselect_b32 s20, s0, s16
	s_cselect_b32 s21, s1, s17
	s_cselect_b32 s18, s8, vcc_lo
	s_cselect_b32 s19, s9, vcc_hi
	s_add_u32 s16, s20, 0x8000
	s_addc_u32 s17, s21, 0
	s_add_i32 s68, 0, 0x10000
	v_add_u32_e32 v36, s68, v148
	s_add_i32 s88, 0, 0x14000
	ds_read_b128 v[152:155], v36
	ds_read_b128 v[156:159], v36 offset:1024
	ds_read_b128 v[160:163], v36 offset:2048
	ds_read_b128 v[164:167], v36 offset:3072
	v_add_u32_e32 v36, s88, v148
	ds_read_b128 v[168:171], v36
	ds_read_b128 v[172:175], v36 offset:1024
	ds_read_b128 v[176:179], v36 offset:2048
	ds_read_b128 v[180:183], v36 offset:3072
	s_add_i32 m0, s27, 0xc000
	ds_read_b128 v[184:187], v150
	ds_read_b128 v[188:191], v150 offset:1024
	ds_read_b128 v[192:195], v150 offset:2048
	ds_read_b128 v[196:199], v150 offset:3072
	ds_read_b128 v[200:203], v150 offset:4096
	ds_read_b128 v[204:207], v150 offset:5120
	ds_read_b128 v[208:211], v150 offset:6144
	ds_read_b128 v[212:215], v150 offset:7168
	global_load_lds_dwordx4 v144, s[10:11]
	s_add_i32 m0, s27, 0xe000
	s_nop 0
	global_load_lds_dwordx4 v146, s[10:11]
	s_waitcnt vmcnt(8)
	s_waitcnt lgkmcnt(0)
	v_mfma_f32_16x16x32_bf16 v[132:135], v[152:155], v[184:187], v[132:135]
	v_mfma_f32_16x16x32_bf16 v[128:131], v[160:163], v[184:187], v[128:131]
	v_mfma_f32_16x16x32_bf16 v[124:127], v[152:155], v[192:195], v[124:127]
	v_mfma_f32_16x16x32_bf16 v[120:123], v[160:163], v[192:195], v[120:123]
	v_mfma_f32_16x16x32_bf16 v[108:111], v[152:155], v[200:203], v[108:111]
	v_mfma_f32_16x16x32_bf16 v[104:107], v[160:163], v[200:203], v[104:107]
	s_barrier
	s_setprio 1
	v_mfma_f32_16x16x32_bf16 v[92:95], v[152:155], v[208:211], v[92:95]
	v_mfma_f32_16x16x32_bf16 v[88:91], v[160:163], v[208:211], v[88:91]
	v_mfma_f32_16x16x32_bf16 v[132:135], v[156:159], v[188:191], v[132:135]
	v_mfma_f32_16x16x32_bf16 v[128:131], v[164:167], v[188:191], v[128:131]
	v_mfma_f32_16x16x32_bf16 v[124:127], v[156:159], v[196:199], v[124:127]
	v_mfma_f32_16x16x32_bf16 v[120:123], v[164:167], v[196:199], v[120:123]
	v_mfma_f32_16x16x32_bf16 v[108:111], v[156:159], v[204:207], v[108:111]
	v_mfma_f32_16x16x32_bf16 v[104:107], v[164:167], v[204:207], v[104:107]
	v_mfma_f32_16x16x32_bf16 v[92:95], v[156:159], v[212:215], v[92:95]
	v_mfma_f32_16x16x32_bf16 v[88:91], v[164:167], v[212:215], v[88:91]
	s_setprio 0
	s_setprio 1
	v_mfma_f32_16x16x32_bf16 v[116:119], v[168:171], v[184:187], v[116:119]
	v_mfma_f32_16x16x32_bf16 v[112:115], v[176:179], v[184:187], v[112:115]
	v_mfma_f32_16x16x32_bf16 v[100:103], v[168:171], v[192:195], v[100:103]
	v_mfma_f32_16x16x32_bf16 v[96:99], v[176:179], v[192:195], v[96:99]
	v_mfma_f32_16x16x32_bf16 v[84:87], v[168:171], v[200:203], v[84:87]
	v_mfma_f32_16x16x32_bf16 v[80:83], v[176:179], v[200:203], v[80:83]
	v_mfma_f32_16x16x32_bf16 v[76:79], v[168:171], v[208:211], v[76:79]
	v_mfma_f32_16x16x32_bf16 v[72:75], v[176:179], v[208:211], v[72:75]
	v_mfma_f32_16x16x32_bf16 v[116:119], v[172:175], v[188:191], v[116:119]
	v_mfma_f32_16x16x32_bf16 v[112:115], v[180:183], v[188:191], v[112:115]
	v_mfma_f32_16x16x32_bf16 v[100:103], v[172:175], v[196:199], v[100:103]
	v_mfma_f32_16x16x32_bf16 v[96:99], v[180:183], v[196:199], v[96:99]
	v_mfma_f32_16x16x32_bf16 v[84:87], v[172:175], v[204:207], v[84:87]
	v_mfma_f32_16x16x32_bf16 v[80:83], v[180:183], v[204:207], v[80:83]
	v_mfma_f32_16x16x32_bf16 v[76:79], v[172:175], v[212:215], v[76:79]
	v_mfma_f32_16x16x32_bf16 v[72:75], v[180:183], v[212:215], v[72:75]
	s_setprio 0
	s_barrier
	s_add_i32 s68, s68, s24
	s_mov_b32 m0, s68
	ds_read_b128 v[184:187], v150 offset:16384
	ds_read_b128 v[188:191], v150 offset:17408
	ds_read_b128 v[192:195], v150 offset:18432
	ds_read_b128 v[196:199], v150 offset:19456
	ds_read_b128 v[200:203], v150 offset:20480
	ds_read_b128 v[204:207], v150 offset:21504
	ds_read_b128 v[208:211], v150 offset:22528
	ds_read_b128 v[212:215], v150 offset:23552
	global_load_lds_dwordx4 v138, s[18:19]
	s_add_i32 m0, s68, 0x2000
	s_add_u32 s68, s18, 0x4000
	s_addc_u32 s69, s19, 0
	s_add_i32 s88, s88, s24
	global_load_lds_dwordx4 v142, s[18:19]
	s_mov_b32 m0, s88
	s_nop 0
	global_load_lds_dwordx4 v138, s[68:69]
	s_add_i32 m0, s88, 0x2000
	s_nop 0
	global_load_lds_dwordx4 v142, s[68:69]
	s_mov_b32 m0, s27
	s_nop 0
	global_load_lds_dwordx4 v136, s[20:21]
	s_mov_b32 m0, s28
	s_nop 0
	global_load_lds_dwordx4 v140, s[20:21]
	s_waitcnt vmcnt(8)
	s_waitcnt lgkmcnt(0)
	v_mfma_f32_16x16x32_bf16 v[68:71], v[152:155], v[184:187], v[68:71]
	v_mfma_f32_16x16x32_bf16 v[64:67], v[160:163], v[184:187], v[64:67]
	v_mfma_f32_16x16x32_bf16 v[60:63], v[152:155], v[192:195], v[60:63]
	v_mfma_f32_16x16x32_bf16 v[56:59], v[160:163], v[192:195], v[56:59]
	v_mfma_f32_16x16x32_bf16 v[44:47], v[152:155], v[200:203], v[44:47]
	v_mfma_f32_16x16x32_bf16 v[40:43], v[160:163], v[200:203], v[40:43]
	s_barrier
; #define PG8_STAGE(bufoff, gbase, voff) do { _Pragma("unroll") for (int _i = 0; _i < 2; ++_i) \
;         __builtin_amdgcn_global_load_lds((const unsigned*)((const char*)(gbase) + (voff)[_i]), (PG8_LAS unsigned*)(lds + (bufoff) + ldsw + _i * 8192), 16, 0, 0); } while (0)
; #define PG8_LDA(dst, b, h) do { _Pragma("unroll") for (int m = 0; m < 4; ++m) _Pragma("unroll") for (int k = 0; k < 2; ++k) dst[m][k] = *(const PG8_LAS bf16x8*)(lds + PG8_SA(b, h) + aoff + m * 2048 + k * 1024); } while (0)
; #define PG8_LDB(dst, b, h) do { _Pragma("unroll") for (int n = 0; n < 2; ++n) _Pragma("unroll") for (int k = 0; k < 2; ++k) dst[n][k] = *(const PG8_LAS bf16x8*)(lds + PG8_SB(b, h) + boff + n * 2048 + k * 1024); } while (0)
; #define PG8_MMA(ai, bj, At, Bt) do { __builtin_amdgcn_s_setprio(1); _Pragma("unroll") for (int m = 0; m < 4; ++m) _Pragma("unroll") for (int n = 0; n < 2; ++n) _Pragma("unroll") for (int k = 0; k < 2; ++k) \
;         acc[ai][bj][m][n] = __builtin_amdgcn_mfma_f32_16x16x32_bf16(Bt[n][k], At[m][k], acc[ai][bj][m][n], 0, 0, 0); __builtin_amdgcn_s_setprio(0); } while (0)
; template <class Epi, class Sched, bool ALIGN_EPI = false, bool SP2 = false, bool ABLK = false, bool BBLK = false>
; __device__ __forceinline__ void gemm_phase(PG8_LAS unsigned char* lds, const Gemm g, const Sched& S, const Epi& E) {
;     ...
;             PG8_LDB(B0, 0, 0); PG8_LDB(B1, 0, 1); PG8_SCHED; PG8_LDA(At, 0, 0); PG8_STAGE(PG8_SA(1, 1), a1 + hstepA, voffA);
;             PG8_WAIT_V(8); PG8_WAIT_L(0); PG8_BAR; PG8_MMA(0, 0, At, B0); PG8_MMA(0, 1, At, B1); PG8_BAR; PG8_SCHED;
;             PG8_LDA(At, 0, 1); PG8_STAGE(PG8_SB(0, 0), b2, voffB); PG8_STAGE(PG8_SB(0, 1), b2 + hstepB, voffB); PG8_STAGE(PG8_SA(0, 0), a2, voffA);
;             PG8_WAIT_V(8); PG8_WAIT_L(0); PG8_BAR; PG8_MMA(1, 0, At, B0); PG8_MMA(1, 1, At, B1); PG8_BAR; PG8_SCHED;
;             PG8_LDB(B0, 1, 0); PG8_LDB(B1, 1, 1); PG8_SCHED; PG8_LDA(At, 1, 0); PG8_STAGE(PG8_SA(0, 1), a2 + hstepA, voffA);
;             PG8_WAIT_V(8); PG8_WAIT_L(0); PG8_BAR; PG8_MMA(0, 0, At, B0); PG8_MMA(0, 1, At, B1); PG8_BAR; PG8_SCHED;
;             PG8_LDA(At, 1, 1); PG8_STAGE(PG8_SB(1, 0), b3, voffB); PG8_STAGE(PG8_SB(1, 1), b3 + hstepB, voffB); PG8_STAGE(PG8_SA(1, 0), a3, voffA);
;             PG8_WAIT_V(8); PG8_WAIT_L(0); PG8_BAR; PG8_MMA(1, 0, At, B0); PG8_MMA(1, 1, At, B1); PG8_BAR; PG8_SCHED;
	s_setprio 1
	v_mfma_f32_16x16x32_bf16 v[24:27], v[152:155], v[208:211], v[24:27]
	v_mfma_f32_16x16x32_bf16 v[20:23], v[160:163], v[208:211], v[20:23]
	v_mfma_f32_16x16x32_bf16 v[68:71], v[156:159], v[188:191], v[68:71]
	v_mfma_f32_16x16x32_bf16 v[64:67], v[164:167], v[188:191], v[64:67]
	v_mfma_f32_16x16x32_bf16 v[60:63], v[156:159], v[196:199], v[60:63]
	v_mfma_f32_16x16x32_bf16 v[56:59], v[164:167], v[196:199], v[56:59]
	v_mfma_f32_16x16x32_bf16 v[44:47], v[156:159], v[204:207], v[44:47]
	v_mfma_f32_16x16x32_bf16 v[40:43], v[164:167], v[204:207], v[40:43]
	v_mfma_f32_16x16x32_bf16 v[24:27], v[156:159], v[212:215], v[24:27]
	v_mfma_f32_16x16x32_bf16 v[20:23], v[164:167], v[212:215], v[20:23]
	s_setprio 0
	s_setprio 1
	v_mfma_f32_16x16x32_bf16 v[52:55], v[168:171], v[184:187], v[52:55]
	v_mfma_f32_16x16x32_bf16 v[48:51], v[176:179], v[184:187], v[48:51]
	v_mfma_f32_16x16x32_bf16 v[32:35], v[168:171], v[192:195], v[32:35]
	v_mfma_f32_16x16x32_bf16 v[28:31], v[176:179], v[192:195], v[28:31]
	v_mfma_f32_16x16x32_bf16 v[16:19], v[168:171], v[200:203], v[16:19]
	v_mfma_f32_16x16x32_bf16 v[12:15], v[176:179], v[200:203], v[12:15]
	v_mfma_f32_16x16x32_bf16 v[8:11], v[168:171], v[208:211], v[8:11]
	v_mfma_f32_16x16x32_bf16 v[4:7], v[176:179], v[208:211], v[4:7]
	v_mfma_f32_16x16x32_bf16 v[52:55], v[172:175], v[188:191], v[52:55]
	v_mfma_f32_16x16x32_bf16 v[48:51], v[180:183], v[188:191], v[48:51]
	v_mfma_f32_16x16x32_bf16 v[32:35], v[172:175], v[196:199], v[32:35]
	v_mfma_f32_16x16x32_bf16 v[28:31], v[180:183], v[196:199], v[28:31]
	v_mfma_f32_16x16x32_bf16 v[16:19], v[172:175], v[204:207], v[16:19]
	v_mfma_f32_16x16x32_bf16 v[12:15], v[180:183], v[204:207], v[12:15]
	v_mfma_f32_16x16x32_bf16 v[8:11], v[172:175], v[212:215], v[8:11]
	v_mfma_f32_16x16x32_bf16 v[4:7], v[180:183], v[212:215], v[4:7]
	s_setprio 0
	s_barrier
	s_add_i32 s68, 0, 0x18000
	v_add_u32_e32 v36, s68, v148
	s_add_i32 s69, 0, 0x1c000
	ds_read_b128 v[152:155], v36
	ds_read_b128 v[156:159], v36 offset:1024
	ds_read_b128 v[160:163], v36 offset:2048
	ds_read_b128 v[164:167], v36 offset:3072
	v_add_u32_e32 v36, s69, v148
	ds_read_b128 v[168:171], v36
	ds_read_b128 v[172:175], v36 offset:1024
	ds_read_b128 v[176:179], v36 offset:2048
	ds_read_b128 v[180:183], v36 offset:3072
	s_add_u32 s20, s20, 0x4000
	s_addc_u32 s21, s21, 0
	s_mov_b32 m0, s29
	ds_read_b128 v[184:187], v150 offset:32768
	ds_read_b128 v[188:191], v150 offset:33792
	ds_read_b128 v[192:195], v150 offset:34816
	ds_read_b128 v[196:199], v150 offset:35840
	ds_read_b128 v[200:203], v150 offset:36864
	ds_read_b128 v[204:207], v150 offset:37888
	ds_read_b128 v[208:211], v150 offset:38912
	ds_read_b128 v[212:215], v150 offset:39936
	global_load_lds_dwordx4 v136, s[20:21]
	s_mov_b32 m0, s30
	s_nop 0
	global_load_lds_dwordx4 v140, s[20:21]
	s_waitcnt vmcnt(8)
	s_waitcnt lgkmcnt(0)
	v_mfma_f32_16x16x32_bf16 v[132:135], v[152:155], v[184:187], v[132:135]
	v_mfma_f32_16x16x32_bf16 v[128:131], v[160:163], v[184:187], v[128:131]
	v_mfma_f32_16x16x32_bf16 v[124:127], v[152:155], v[192:195], v[124:127]
	v_mfma_f32_16x16x32_bf16 v[120:123], v[160:163], v[192:195], v[120:123]
	v_mfma_f32_16x16x32_bf16 v[108:111], v[152:155], v[200:203], v[108:111]
	v_mfma_f32_16x16x32_bf16 v[104:107], v[160:163], v[200:203], v[104:107]
	s_barrier
	s_setprio 1
	v_mfma_f32_16x16x32_bf16 v[92:95], v[152:155], v[208:211], v[92:95]
	v_mfma_f32_16x16x32_bf16 v[88:91], v[160:163], v[208:211], v[88:91]
	v_mfma_f32_16x16x32_bf16 v[132:135], v[156:159], v[188:191], v[132:135]
	v_mfma_f32_16x16x32_bf16 v[128:131], v[164:167], v[188:191], v[128:131]
	v_mfma_f32_16x16x32_bf16 v[124:127], v[156:159], v[196:199], v[124:127]
	v_mfma_f32_16x16x32_bf16 v[120:123], v[164:167], v[196:199], v[120:123]
	v_mfma_f32_16x16x32_bf16 v[108:111], v[156:159], v[204:207], v[108:111]
	v_mfma_f32_16x16x32_bf16 v[104:107], v[164:167], v[204:207], v[104:107]
	v_mfma_f32_16x16x32_bf16 v[92:95], v[156:159], v[212:215], v[92:95]
	v_mfma_f32_16x16x32_bf16 v[88:91], v[164:167], v[212:215], v[88:91]
	s_setprio 0
	s_setprio 1
	v_mfma_f32_16x16x32_bf16 v[116:119], v[168:171], v[184:187], v[116:119]
	v_mfma_f32_16x16x32_bf16 v[112:115], v[176:179], v[184:187], v[112:115]
	v_mfma_f32_16x16x32_bf16 v[100:103], v[168:171], v[192:195], v[100:103]
	v_mfma_f32_16x16x32_bf16 v[96:99], v[176:179], v[192:195], v[96:99]
	v_mfma_f32_16x16x32_bf16 v[84:87], v[168:171], v[200:203], v[84:87]
	v_mfma_f32_16x16x32_bf16 v[80:83], v[176:179], v[200:203], v[80:83]
	v_mfma_f32_16x16x32_bf16 v[76:79], v[168:171], v[208:211], v[76:79]
	v_mfma_f32_16x16x32_bf16 v[72:75], v[176:179], v[208:211], v[72:75]
	v_mfma_f32_16x16x32_bf16 v[116:119], v[172:175], v[188:191], v[116:119]
	v_mfma_f32_16x16x32_bf16 v[112:115], v[180:183], v[188:191], v[112:115]
	v_mfma_f32_16x16x32_bf16 v[100:103], v[172:175], v[196:199], v[100:103]
	v_mfma_f32_16x16x32_bf16 v[96:99], v[180:183], v[196:199], v[96:99]
	v_mfma_f32_16x16x32_bf16 v[84:87], v[172:175], v[204:207], v[84:87]
	v_mfma_f32_16x16x32_bf16 v[80:83], v[180:183], v[204:207], v[80:83]
	v_mfma_f32_16x16x32_bf16 v[76:79], v[172:175], v[212:215], v[76:79]
	v_mfma_f32_16x16x32_bf16 v[72:75], v[180:183], v[212:215], v[72:75]
	s_setprio 0
	s_barrier
; #define PG8_STAGE(bufoff, gbase, voff) do { _Pragma("unroll") for (int _i = 0; _i < 2; ++_i) \
;         __builtin_amdgcn_global_load_lds((const unsigned*)((const char*)(gbase) + (voff)[_i]), (PG8_LAS unsigned*)(lds + (bufoff) + ldsw + _i * 8192), 16, 0, 0); } while (0)
; #define PG8_LDA(dst, b, h) do { _Pragma("unroll") for (int m = 0; m < 4; ++m) _Pragma("unroll") for (int k = 0; k < 2; ++k) dst[m][k] = *(const PG8_LAS bf16x8*)(lds + PG8_SA(b, h) + aoff + m * 2048 + k * 1024); } while (0)
; #define PG8_LDB(dst, b, h) do { _Pragma("unroll") for (int n = 0; n < 2; ++n) _Pragma("unroll") for (int k = 0; k < 2; ++k) dst[n][k] = *(const PG8_LAS bf16x8*)(lds + PG8_SB(b, h) + boff + n * 2048 + k * 1024); } while (0)
; #define PG8_MMA(ai, bj, At, Bt) do { __builtin_amdgcn_s_setprio(1); _Pragma("unroll") for (int m = 0; m < 4; ++m) _Pragma("unroll") for (int n = 0; n < 2; ++n) _Pragma("unroll") for (int k = 0; k < 2; ++k) \
;         acc[ai][bj][m][n] = __builtin_amdgcn_mfma_f32_16x16x32_bf16(Bt[n][k], At[m][k], acc[ai][bj][m][n], 0, 0, 0); __builtin_amdgcn_s_setprio(0); } while (0)
; #define PG8_WAIT_V(n) asm volatile("s_waitcnt vmcnt(" #n ")" ::: "memory")
; #define PG8_WAIT_L(n) asm volatile("s_waitcnt lgkmcnt(" #n ")" ::: "memory")
; #define PG8_BAR __builtin_amdgcn_s_barrier()
; template <class Epi, class Sched, bool ALIGN_EPI = false, bool SP2 = false, bool ABLK = false, bool BBLK = false>
; __device__ __forceinline__ void gemm_phase(PG8_LAS unsigned char* lds, const Gemm g, const Sched& S, const Epi& E) {
;     ...
;         for (int t = 0; t < nt; t += 2) {
;             const bool last = (t == nt - 2);
;             const char* a1 = cA + (size_t)(t + 1) * kstepA;
;             const char* a2 = last ? nA : cA + (size_t)(t + 2) * kstepA; const char* b2 = last ? nB : cB + (size_t)(t + 2) * kstepB;
;     ...
;             PG8_LDB(B0, 1, 0); PG8_LDB(B1, 1, 1); PG8_SCHED; PG8_LDA(At, 1, 0); PG8_STAGE(PG8_SA(0, 1), a2 + hstepA, voffA);
;             PG8_WAIT_V(8); PG8_WAIT_L(0); PG8_BAR; PG8_MMA(0, 0, At, B0); PG8_MMA(0, 1, At, B1); PG8_BAR; PG8_SCHED;
;             PG8_LDA(At, 1, 1); PG8_STAGE(PG8_SB(1, 0), b3, voffB); PG8_STAGE(PG8_SB(1, 1), b3 + hstepB, voffB); PG8_STAGE(PG8_SA(1, 0), a3, voffA);
;             PG8_WAIT_V(8); PG8_WAIT_L(0); PG8_BAR; PG8_MMA(1, 0, At, B0); PG8_MMA(1, 1, At, B1); PG8_BAR; PG8_SCHED;
;     ...
;         if constexpr (ALIGN_EPI) { if (wr == 0) PG8_BAR; }
	s_add_u32 s20, s18, 0x8000
	s_addc_u32 s21, s19, 0
	s_add_i32 s68, s68, s24
	s_mov_b32 m0, s68
	ds_read_b128 v[184:187], v150 offset:49152
	ds_read_b128 v[188:191], v150 offset:50176
	ds_read_b128 v[192:195], v150 offset:51200
	ds_read_b128 v[196:199], v150 offset:52224
	ds_read_b128 v[200:203], v150 offset:53248
	ds_read_b128 v[204:207], v150 offset:54272
	ds_read_b128 v[208:211], v150 offset:55296
	ds_read_b128 v[212:215], v150 offset:56320
	global_load_lds_dwordx4 v138, s[20:21]
	s_add_i32 m0, s68, 0x2000
	s_add_u32 s18, s18, 0xc000
	s_addc_u32 s19, s19, 0
	global_load_lds_dwordx4 v142, s[20:21]
	s_add_i32 s20, s69, s24
	s_mov_b32 m0, s20
	s_nop 0
	global_load_lds_dwordx4 v138, s[18:19]
	s_add_i32 m0, s20, 0x2000
	s_nop 0
	global_load_lds_dwordx4 v142, s[18:19]
	s_mov_b32 m0, s35
	s_nop 0
	global_load_lds_dwordx4 v136, s[16:17]
	s_mov_b32 m0, s70
	s_nop 0
	global_load_lds_dwordx4 v140, s[16:17]
	s_waitcnt vmcnt(8)
	s_waitcnt lgkmcnt(0)
	v_mfma_f32_16x16x32_bf16 v[68:71], v[152:155], v[184:187], v[68:71]
	v_mfma_f32_16x16x32_bf16 v[64:67], v[160:163], v[184:187], v[64:67]
	v_mfma_f32_16x16x32_bf16 v[60:63], v[152:155], v[192:195], v[60:63]
	v_mfma_f32_16x16x32_bf16 v[56:59], v[160:163], v[192:195], v[56:59]
	v_mfma_f32_16x16x32_bf16 v[44:47], v[152:155], v[200:203], v[44:47]
	v_mfma_f32_16x16x32_bf16 v[40:43], v[160:163], v[200:203], v[40:43]
	s_barrier
	s_setprio 1
	v_mfma_f32_16x16x32_bf16 v[24:27], v[152:155], v[208:211], v[24:27]
	v_mfma_f32_16x16x32_bf16 v[20:23], v[160:163], v[208:211], v[20:23]
	v_mfma_f32_16x16x32_bf16 v[68:71], v[156:159], v[188:191], v[68:71]
	v_mfma_f32_16x16x32_bf16 v[64:67], v[164:167], v[188:191], v[64:67]
	v_mfma_f32_16x16x32_bf16 v[60:63], v[156:159], v[196:199], v[60:63]
	v_mfma_f32_16x16x32_bf16 v[56:59], v[164:167], v[196:199], v[56:59]
	v_mfma_f32_16x16x32_bf16 v[44:47], v[156:159], v[204:207], v[44:47]
	v_mfma_f32_16x16x32_bf16 v[40:43], v[164:167], v[204:207], v[40:43]
	v_mfma_f32_16x16x32_bf16 v[24:27], v[156:159], v[212:215], v[24:27]
	v_mfma_f32_16x16x32_bf16 v[20:23], v[164:167], v[212:215], v[20:23]
	s_setprio 0
	s_setprio 1
	v_mfma_f32_16x16x32_bf16 v[52:55], v[168:171], v[184:187], v[52:55]
	v_mfma_f32_16x16x32_bf16 v[48:51], v[176:179], v[184:187], v[48:51]
	v_mfma_f32_16x16x32_bf16 v[32:35], v[168:171], v[192:195], v[32:35]
	v_mfma_f32_16x16x32_bf16 v[28:31], v[176:179], v[192:195], v[28:31]
	v_mfma_f32_16x16x32_bf16 v[16:19], v[168:171], v[200:203], v[16:19]
	v_mfma_f32_16x16x32_bf16 v[12:15], v[176:179], v[200:203], v[12:15]
	v_mfma_f32_16x16x32_bf16 v[8:11], v[168:171], v[208:211], v[8:11]
	v_mfma_f32_16x16x32_bf16 v[4:7], v[176:179], v[208:211], v[4:7]
	v_mfma_f32_16x16x32_bf16 v[52:55], v[172:175], v[188:191], v[52:55]
	v_mfma_f32_16x16x32_bf16 v[48:51], v[180:183], v[188:191], v[48:51]
	v_mfma_f32_16x16x32_bf16 v[32:35], v[172:175], v[196:199], v[32:35]
	v_mfma_f32_16x16x32_bf16 v[28:31], v[180:183], v[196:199], v[28:31]
	v_mfma_f32_16x16x32_bf16 v[16:19], v[172:175], v[204:207], v[16:19]
	v_mfma_f32_16x16x32_bf16 v[12:15], v[180:183], v[204:207], v[12:15]
	v_mfma_f32_16x16x32_bf16 v[8:11], v[172:175], v[212:215], v[8:11]
	v_mfma_f32_16x16x32_bf16 v[4:7], v[180:183], v[212:215], v[4:7]
	s_setprio 0
	s_barrier
	s_add_i32 s13, s13, 2
	s_add_u32 s10, s10, 0x10000
	s_addc_u32 s11, s11, 0
	s_add_u32 vcc_lo, vcc_lo, 0x10000
	s_addc_u32 vcc_hi, vcc_hi, 0
	s_cmpk_gt_u32 s13, 0x55
	s_cbranch_scc0 .LBB0_439
	s_and_b64 vcc, exec, s[6:7]
	s_cbranch_vccz .LBB0_442
	s_barrier

; #define PG8_STAGE(bufoff, gbase, voff) do { _Pragma("unroll") for (int _i = 0; _i < 2; ++_i) \
;         __builtin_amdgcn_global_load_lds((const unsigned*)((const char*)(gbase) + (voff)[_i]), (PG8_LAS unsigned*)(lds + (bufoff) + ldsw + _i * 8192), 16, 0, 0); } while (0)
; #define PG8_LDA(dst, b, h) do { _Pragma("unroll") for (int m = 0; m < 4; ++m) _Pragma("unroll") for (int k = 0; k < 2; ++k) dst[m][k] = *(const PG8_LAS bf16x8*)(lds + PG8_SA(b, h) + aoff + m * 2048 + k * 1024); } while (0)
; #define PG8_WAIT_V(n) asm volatile("s_waitcnt vmcnt(" #n ")" ::: "memory")
; #define PG8_WAIT_L(n) asm volatile("s_waitcnt lgkmcnt(" #n ")" ::: "memory")
; template <class Epi, class Sched, bool ALIGN_EPI = false, bool SP2 = false, bool ABLK = false, bool BBLK = false>
; __device__ __forceinline__ void gemm_phase(PG8_LAS unsigned char* lds, const Gemm g, const Sched& S, const Epi& E) {
;     ...
;         for (int t = 0; t < nt; t += 2) {
;             const bool last = (t == nt - 2);
;             const char* a1 = cA + (size_t)(t + 1) * kstepA;
;             const char* a2 = last ? nA : cA + (size_t)(t + 2) * kstepA; const char* b2 = last ? nB : cB + (size_t)(t + 2) * kstepB;
;             const char* a3 = a2 + kstepA; const char* b3 = b2 + kstepB;
;             if (last && has_next) S.a_ready(nxt);
;             if constexpr (SP2) {
;             PG8_LDB(B0, 0, 0); PG8_LDB(B1, 0, 1); PG8_SCHED; PG8_LDA(At, 0, 0); PG8_STAGE(PG8_SA(1, 1), a1 + hstepA, voffA);
;             PG8_WAIT_V(8); PG8_WAIT_L(0); PG8_BAR; PG8_MMA(0, 0, At, B0); PG8_MMA(0, 1, At, B1); PG8_BAR; PG8_SCHED;
;             PG8_LDA(At, 0, 1); PG8_STAGE(PG8_SB(0, 0), b2, voffB); PG8_STAGE(PG8_SB(0, 1), b2 + hstepB, voffB); PG8_STAGE(PG8_SA(0, 0), a2, voffA);
;             PG8_WAIT_V(8); PG8_WAIT_L(0); PG8_BAR; PG8_MMA(1, 0, At, B0); PG8_MMA(1, 1, At, B1); PG8_BAR; PG8_SCHED;
;             PG8_LDB(B0, 1, 0); PG8_LDB(B1, 1, 1); PG8_SCHED; PG8_LDA(At, 1, 0); PG8_STAGE(PG8_SA(0, 1), a2 + hstepA, voffA);
;             PG8_WAIT_V(8); PG8_WAIT_L(0); PG8_BAR; PG8_MMA(0, 0, At, B0); PG8_MMA(0, 1, At, B1); PG8_BAR; PG8_SCHED;
;             PG8_LDA(At, 1, 1); PG8_STAGE(PG8_SB(1, 0), b3, voffB); PG8_STAGE(PG8_SB(1, 1), b3 + hstepB, voffB); PG8_STAGE(PG8_SA(1, 0), a3, voffA);
;             PG8_WAIT_V(8); PG8_WAIT_L(0); PG8_BAR; PG8_MMA(1, 0, At, B0); PG8_MMA(1, 1, At, B1); PG8_BAR; PG8_SCHED;
.LBB0_916:
	s_add_u32 s22, s20, 0x4000
	s_addc_u32 s23, s21, 0
	s_cmp_eq_u32 s13, 28
	s_cselect_b32 s26, s19, s22
	s_cselect_b32 s27, s1, s23
	s_cselect_b32 s24, s65, s70
	s_cselect_b32 s25, s9, s71
	s_add_u32 s22, s26, 0x8000
	s_addc_u32 s23, s27, 0
	s_add_i32 s68, 0, 0x10000
	v_add_u32_e32 v36, s68, v155
	s_add_i32 s77, 0, 0x14000
	ds_read_b128 v[150:153], v36
	ds_read_b128 v[158:161], v36 offset:1024
	ds_read_b128 v[162:165], v36 offset:2048
	ds_read_b128 v[166:169], v36 offset:3072
	v_add_u32_e32 v36, s77, v155
	ds_read_b128 v[170:173], v36
	ds_read_b128 v[174:177], v36 offset:1024
	ds_read_b128 v[178:181], v36 offset:2048
	ds_read_b128 v[182:185], v36 offset:3072
	s_add_i32 m0, s31, 0xc000
	ds_read_b128 v[186:189], v157
	ds_read_b128 v[190:193], v157 offset:1024
	ds_read_b128 v[194:197], v157 offset:2048
	ds_read_b128 v[198:201], v157 offset:3072
	ds_read_b128 v[202:205], v157 offset:4096
	ds_read_b128 v[206:209], v157 offset:5120
	ds_read_b128 v[210:213], v157 offset:6144
	ds_read_b128 v[214:217], v157 offset:7168
	global_load_lds_dwordx4 v146, s[20:21]
	s_add_i32 m0, s31, 0xe000
	s_nop 0
	global_load_lds_dwordx4 v148, s[20:21]
	s_waitcnt vmcnt(8)
	s_waitcnt lgkmcnt(0)
	v_mfma_f32_16x16x32_bf16 v[132:135], v[150:153], v[186:189], v[132:135]
	v_mfma_f32_16x16x32_bf16 v[128:131], v[162:165], v[186:189], v[128:131]
	v_mfma_f32_16x16x32_bf16 v[124:127], v[150:153], v[194:197], v[124:127]
	v_mfma_f32_16x16x32_bf16 v[116:119], v[162:165], v[194:197], v[116:119]
	v_mfma_f32_16x16x32_bf16 v[108:111], v[150:153], v[202:205], v[108:111]
	v_mfma_f32_16x16x32_bf16 v[100:103], v[162:165], v[202:205], v[100:103]
	s_barrier
	s_setprio 1
	v_mfma_f32_16x16x32_bf16 v[92:95], v[150:153], v[210:213], v[92:95]
	v_mfma_f32_16x16x32_bf16 v[84:87], v[162:165], v[210:213], v[84:87]
	v_mfma_f32_16x16x32_bf16 v[132:135], v[158:161], v[190:193], v[132:135]
	v_mfma_f32_16x16x32_bf16 v[128:131], v[166:169], v[190:193], v[128:131]
	v_mfma_f32_16x16x32_bf16 v[124:127], v[158:161], v[198:201], v[124:127]
	v_mfma_f32_16x16x32_bf16 v[116:119], v[166:169], v[198:201], v[116:119]
	v_mfma_f32_16x16x32_bf16 v[108:111], v[158:161], v[206:209], v[108:111]
	v_mfma_f32_16x16x32_bf16 v[100:103], v[166:169], v[206:209], v[100:103]
	v_mfma_f32_16x16x32_bf16 v[92:95], v[158:161], v[214:217], v[92:95]
	v_mfma_f32_16x16x32_bf16 v[84:87], v[166:169], v[214:217], v[84:87]
	s_setprio 0
	s_setprio 1
	v_mfma_f32_16x16x32_bf16 v[120:123], v[170:173], v[186:189], v[120:123]
	v_mfma_f32_16x16x32_bf16 v[112:115], v[178:181], v[186:189], v[112:115]
	v_mfma_f32_16x16x32_bf16 v[104:107], v[170:173], v[194:197], v[104:107]
	v_mfma_f32_16x16x32_bf16 v[96:99], v[178:181], v[194:197], v[96:99]
	v_mfma_f32_16x16x32_bf16 v[88:91], v[170:173], v[202:205], v[88:91]
	v_mfma_f32_16x16x32_bf16 v[80:83], v[178:181], v[202:205], v[80:83]
	v_mfma_f32_16x16x32_bf16 v[76:79], v[170:173], v[210:213], v[76:79]
	v_mfma_f32_16x16x32_bf16 v[72:75], v[178:181], v[210:213], v[72:75]
	v_mfma_f32_16x16x32_bf16 v[120:123], v[174:177], v[190:193], v[120:123]
	v_mfma_f32_16x16x32_bf16 v[112:115], v[182:185], v[190:193], v[112:115]
	v_mfma_f32_16x16x32_bf16 v[104:107], v[174:177], v[198:201], v[104:107]
	v_mfma_f32_16x16x32_bf16 v[96:99], v[182:185], v[198:201], v[96:99]
	v_mfma_f32_16x16x32_bf16 v[88:91], v[174:177], v[206:209], v[88:91]
	v_mfma_f32_16x16x32_bf16 v[80:83], v[182:185], v[206:209], v[80:83]
	v_mfma_f32_16x16x32_bf16 v[76:79], v[174:177], v[214:217], v[76:79]
	v_mfma_f32_16x16x32_bf16 v[72:75], v[182:185], v[214:217], v[72:75]
	s_setprio 0
	s_barrier
	s_add_i32 s68, s68, s29
	s_mov_b32 m0, s68
	ds_read_b128 v[186:189], v157 offset:16384
	ds_read_b128 v[190:193], v157 offset:17408
	ds_read_b128 v[194:197], v157 offset:18432
	ds_read_b128 v[198:201], v157 offset:19456
	ds_read_b128 v[202:205], v157 offset:20480
	ds_read_b128 v[206:209], v157 offset:21504
	ds_read_b128 v[210:213], v157 offset:22528
	ds_read_b128 v[214:217], v157 offset:23552
	global_load_lds_dwordx4 v140, s[24:25]
	s_add_i32 m0, s68, 0x2000
	s_add_u32 s68, s24, 0x4000
	s_addc_u32 s69, s25, 0
	s_add_i32 s77, s77, s29
	global_load_lds_dwordx4 v136, s[24:25]
	s_mov_b32 m0, s77
	s_nop 0
	global_load_lds_dwordx4 v140, s[68:69]
	s_add_i32 m0, s77, 0x2000
	s_nop 0
	global_load_lds_dwordx4 v136, s[68:69]
	s_mov_b32 m0, s31
	s_nop 0
	global_load_lds_dwordx4 v142, s[26:27]
	s_mov_b32 m0, s34
	s_nop 0
	global_load_lds_dwordx4 v138, s[26:27]
	s_waitcnt vmcnt(8)
	s_waitcnt lgkmcnt(0)
	v_mfma_f32_16x16x32_bf16 v[68:71], v[150:153], v[186:189], v[68:71]
	v_mfma_f32_16x16x32_bf16 v[64:67], v[162:165], v[186:189], v[64:67]
	v_mfma_f32_16x16x32_bf16 v[60:63], v[150:153], v[194:197], v[60:63]
	v_mfma_f32_16x16x32_bf16 v[52:55], v[162:165], v[194:197], v[52:55]
	v_mfma_f32_16x16x32_bf16 v[44:47], v[150:153], v[202:205], v[44:47]
	v_mfma_f32_16x16x32_bf16 v[32:35], v[162:165], v[202:205], v[32:35]
	s_barrier
; #define PG8_STAGE(bufoff, gbase, voff) do { _Pragma("unroll") for (int _i = 0; _i < 2; ++_i) \
;         __builtin_amdgcn_global_load_lds((const unsigned*)((const char*)(gbase) + (voff)[_i]), (PG8_LAS unsigned*)(lds + (bufoff) + ldsw + _i * 8192), 16, 0, 0); } while (0)
; #define PG8_LDA(dst, b, h) do { _Pragma("unroll") for (int m = 0; m < 4; ++m) _Pragma("unroll") for (int k = 0; k < 2; ++k) dst[m][k] = *(const PG8_LAS bf16x8*)(lds + PG8_SA(b, h) + aoff + m * 2048 + k * 1024); } while (0)
; #define PG8_LDB(dst, b, h) do { _Pragma("unroll") for (int n = 0; n < 2; ++n) _Pragma("unroll") for (int k = 0; k < 2; ++k) dst[n][k] = *(const PG8_LAS bf16x8*)(lds + PG8_SB(b, h) + boff + n * 2048 + k * 1024); } while (0)
; #define PG8_MMA(ai, bj, At, Bt) do { __builtin_amdgcn_s_setprio(1); _Pragma("unroll") for (int m = 0; m < 4; ++m) _Pragma("unroll") for (int n = 0; n < 2; ++n) _Pragma("unroll") for (int k = 0; k < 2; ++k) \
;         acc[ai][bj][m][n] = __builtin_amdgcn_mfma_f32_16x16x32_bf16(Bt[n][k], At[m][k], acc[ai][bj][m][n], 0, 0, 0); __builtin_amdgcn_s_setprio(0); } while (0)
; template <class Epi, class Sched, bool ALIGN_EPI = false, bool SP2 = false, bool ABLK = false, bool BBLK = false>
; __device__ __forceinline__ void gemm_phase(PG8_LAS unsigned char* lds, const Gemm g, const Sched& S, const Epi& E) {
;     ...
;             PG8_LDB(B0, 0, 0); PG8_LDB(B1, 0, 1); PG8_SCHED; PG8_LDA(At, 0, 0); PG8_STAGE(PG8_SA(1, 1), a1 + hstepA, voffA);
;             PG8_WAIT_V(8); PG8_WAIT_L(0); PG8_BAR; PG8_MMA(0, 0, At, B0); PG8_MMA(0, 1, At, B1); PG8_BAR; PG8_SCHED;
;             PG8_LDA(At, 0, 1); PG8_STAGE(PG8_SB(0, 0), b2, voffB); PG8_STAGE(PG8_SB(0, 1), b2 + hstepB, voffB); PG8_STAGE(PG8_SA(0, 0), a2, voffA);
;             PG8_WAIT_V(8); PG8_WAIT_L(0); PG8_BAR; PG8_MMA(1, 0, At, B0); PG8_MMA(1, 1, At, B1); PG8_BAR; PG8_SCHED;
;             PG8_LDB(B0, 1, 0); PG8_LDB(B1, 1, 1); PG8_SCHED; PG8_LDA(At, 1, 0); PG8_STAGE(PG8_SA(0, 1), a2 + hstepA, voffA);
;             PG8_WAIT_V(8); PG8_WAIT_L(0); PG8_BAR; PG8_MMA(0, 0, At, B0); PG8_MMA(0, 1, At, B1); PG8_BAR; PG8_SCHED;
;             PG8_LDA(At, 1, 1); PG8_STAGE(PG8_SB(1, 0), b3, voffB); PG8_STAGE(PG8_SB(1, 1), b3 + hstepB, voffB); PG8_STAGE(PG8_SA(1, 0), a3, voffA);
;             PG8_WAIT_V(8); PG8_WAIT_L(0); PG8_BAR; PG8_MMA(1, 0, At, B0); PG8_MMA(1, 1, At, B1); PG8_BAR; PG8_SCHED;
	s_setprio 1
	v_mfma_f32_16x16x32_bf16 v[24:27], v[150:153], v[210:213], v[24:27]
	v_mfma_f32_16x16x32_bf16 v[16:19], v[162:165], v[210:213], v[16:19]
	v_mfma_f32_16x16x32_bf16 v[68:71], v[158:161], v[190:193], v[68:71]
	v_mfma_f32_16x16x32_bf16 v[64:67], v[166:169], v[190:193], v[64:67]
	v_mfma_f32_16x16x32_bf16 v[60:63], v[158:161], v[198:201], v[60:63]
	v_mfma_f32_16x16x32_bf16 v[52:55], v[166:169], v[198:201], v[52:55]
	v_mfma_f32_16x16x32_bf16 v[44:47], v[158:161], v[206:209], v[44:47]
	v_mfma_f32_16x16x32_bf16 v[32:35], v[166:169], v[206:209], v[32:35]
	v_mfma_f32_16x16x32_bf16 v[24:27], v[158:161], v[214:217], v[24:27]
	v_mfma_f32_16x16x32_bf16 v[16:19], v[166:169], v[214:217], v[16:19]
	s_setprio 0
	s_setprio 1
	v_mfma_f32_16x16x32_bf16 v[56:59], v[170:173], v[186:189], v[56:59]
	v_mfma_f32_16x16x32_bf16 v[48:51], v[178:181], v[186:189], v[48:51]
	v_mfma_f32_16x16x32_bf16 v[40:43], v[170:173], v[194:197], v[40:43]
	v_mfma_f32_16x16x32_bf16 v[28:31], v[178:181], v[194:197], v[28:31]
	v_mfma_f32_16x16x32_bf16 v[20:23], v[170:173], v[202:205], v[20:23]
	v_mfma_f32_16x16x32_bf16 v[12:15], v[178:181], v[202:205], v[12:15]
	v_mfma_f32_16x16x32_bf16 v[8:11], v[170:173], v[210:213], v[8:11]
	v_mfma_f32_16x16x32_bf16 v[4:7], v[178:181], v[210:213], v[4:7]
	v_mfma_f32_16x16x32_bf16 v[56:59], v[174:177], v[190:193], v[56:59]
	v_mfma_f32_16x16x32_bf16 v[48:51], v[182:185], v[190:193], v[48:51]
	v_mfma_f32_16x16x32_bf16 v[40:43], v[174:177], v[198:201], v[40:43]
	v_mfma_f32_16x16x32_bf16 v[28:31], v[182:185], v[198:201], v[28:31]
	v_mfma_f32_16x16x32_bf16 v[20:23], v[174:177], v[206:209], v[20:23]
	v_mfma_f32_16x16x32_bf16 v[12:15], v[182:185], v[206:209], v[12:15]
	v_mfma_f32_16x16x32_bf16 v[8:11], v[174:177], v[214:217], v[8:11]
	v_mfma_f32_16x16x32_bf16 v[4:7], v[182:185], v[214:217], v[4:7]
	s_setprio 0
	s_barrier
	s_add_i32 s68, 0, 0x18000
	v_add_u32_e32 v36, s68, v155
	s_add_i32 s69, 0, 0x1c000
	ds_read_b128 v[150:153], v36
	ds_read_b128 v[158:161], v36 offset:1024
	ds_read_b128 v[162:165], v36 offset:2048
	ds_read_b128 v[166:169], v36 offset:3072
	v_add_u32_e32 v36, s69, v155
	ds_read_b128 v[170:173], v36
	ds_read_b128 v[174:177], v36 offset:1024
	ds_read_b128 v[178:181], v36 offset:2048
	ds_read_b128 v[182:185], v36 offset:3072
	s_add_u32 s26, s26, 0x4000
	s_addc_u32 s27, s27, 0
	s_mov_b32 m0, s35
	ds_read_b128 v[186:189], v157 offset:32768
	ds_read_b128 v[190:193], v157 offset:33792
	ds_read_b128 v[194:197], v157 offset:34816
	ds_read_b128 v[198:201], v157 offset:35840
	ds_read_b128 v[202:205], v157 offset:36864
	ds_read_b128 v[206:209], v157 offset:37888
	ds_read_b128 v[210:213], v157 offset:38912
	ds_read_b128 v[214:217], v157 offset:39936
	global_load_lds_dwordx4 v142, s[26:27]
	s_mov_b32 m0, s36
	s_nop 0
	global_load_lds_dwordx4 v138, s[26:27]
	s_waitcnt vmcnt(8)
	s_waitcnt lgkmcnt(0)
	v_mfma_f32_16x16x32_bf16 v[132:135], v[150:153], v[186:189], v[132:135]
	v_mfma_f32_16x16x32_bf16 v[128:131], v[162:165], v[186:189], v[128:131]
	v_mfma_f32_16x16x32_bf16 v[124:127], v[150:153], v[194:197], v[124:127]
	v_mfma_f32_16x16x32_bf16 v[116:119], v[162:165], v[194:197], v[116:119]
	v_mfma_f32_16x16x32_bf16 v[108:111], v[150:153], v[202:205], v[108:111]
	v_mfma_f32_16x16x32_bf16 v[100:103], v[162:165], v[202:205], v[100:103]
	s_barrier
	s_setprio 1
	v_mfma_f32_16x16x32_bf16 v[92:95], v[150:153], v[210:213], v[92:95]
	v_mfma_f32_16x16x32_bf16 v[84:87], v[162:165], v[210:213], v[84:87]
	v_mfma_f32_16x16x32_bf16 v[132:135], v[158:161], v[190:193], v[132:135]
	v_mfma_f32_16x16x32_bf16 v[128:131], v[166:169], v[190:193], v[128:131]
	v_mfma_f32_16x16x32_bf16 v[124:127], v[158:161], v[198:201], v[124:127]
	v_mfma_f32_16x16x32_bf16 v[116:119], v[166:169], v[198:201], v[116:119]
	v_mfma_f32_16x16x32_bf16 v[108:111], v[158:161], v[206:209], v[108:111]
	v_mfma_f32_16x16x32_bf16 v[100:103], v[166:169], v[206:209], v[100:103]
	v_mfma_f32_16x16x32_bf16 v[92:95], v[158:161], v[214:217], v[92:95]
	v_mfma_f32_16x16x32_bf16 v[84:87], v[166:169], v[214:217], v[84:87]
	s_setprio 0
	s_setprio 1
	v_mfma_f32_16x16x32_bf16 v[120:123], v[170:173], v[186:189], v[120:123]
	v_mfma_f32_16x16x32_bf16 v[112:115], v[178:181], v[186:189], v[112:115]
	v_mfma_f32_16x16x32_bf16 v[104:107], v[170:173], v[194:197], v[104:107]
	v_mfma_f32_16x16x32_bf16 v[96:99], v[178:181], v[194:197], v[96:99]
	v_mfma_f32_16x16x32_bf16 v[88:91], v[170:173], v[202:205], v[88:91]
	v_mfma_f32_16x16x32_bf16 v[80:83], v[178:181], v[202:205], v[80:83]
	v_mfma_f32_16x16x32_bf16 v[76:79], v[170:173], v[210:213], v[76:79]
	v_mfma_f32_16x16x32_bf16 v[72:75], v[178:181], v[210:213], v[72:75]
	v_mfma_f32_16x16x32_bf16 v[120:123], v[174:177], v[190:193], v[120:123]
	v_mfma_f32_16x16x32_bf16 v[112:115], v[182:185], v[190:193], v[112:115]
	v_mfma_f32_16x16x32_bf16 v[104:107], v[174:177], v[198:201], v[104:107]
	v_mfma_f32_16x16x32_bf16 v[96:99], v[182:185], v[198:201], v[96:99]
	v_mfma_f32_16x16x32_bf16 v[88:91], v[174:177], v[206:209], v[88:91]
	v_mfma_f32_16x16x32_bf16 v[80:83], v[182:185], v[206:209], v[80:83]
	v_mfma_f32_16x16x32_bf16 v[76:79], v[174:177], v[214:217], v[76:79]
	v_mfma_f32_16x16x32_bf16 v[72:75], v[182:185], v[214:217], v[72:75]
	s_setprio 0
	s_barrier
; #define PG8_STAGE(bufoff, gbase, voff) do { _Pragma("unroll") for (int _i = 0; _i < 2; ++_i) \
;         __builtin_amdgcn_global_load_lds((const unsigned*)((const char*)(gbase) + (voff)[_i]), (PG8_LAS unsigned*)(lds + (bufoff) + ldsw + _i * 8192), 16, 0, 0); } while (0)
; #define PG8_LDA(dst, b, h) do { _Pragma("unroll") for (int m = 0; m < 4; ++m) _Pragma("unroll") for (int k = 0; k < 2; ++k) dst[m][k] = *(const PG8_LAS bf16x8*)(lds + PG8_SA(b, h) + aoff + m * 2048 + k * 1024); } while (0)
; #define PG8_MMA(ai, bj, At, Bt) do { __builtin_amdgcn_s_setprio(1); _Pragma("unroll") for (int m = 0; m < 4; ++m) _Pragma("unroll") for (int n = 0; n < 2; ++n) _Pragma("unroll") for (int k = 0; k < 2; ++k) \
;         acc[ai][bj][m][n] = __builtin_amdgcn_mfma_f32_16x16x32_bf16(Bt[n][k], At[m][k], acc[ai][bj][m][n], 0, 0, 0); __builtin_amdgcn_s_setprio(0); } while (0)
; #define PG8_WAIT_V(n) asm volatile("s_waitcnt vmcnt(" #n ")" ::: "memory")
; #define PG8_WAIT_L(n) asm volatile("s_waitcnt lgkmcnt(" #n ")" ::: "memory")
; #define PG8_BAR __builtin_amdgcn_s_barrier()
; #define PG8_SCHED __builtin_amdgcn_sched_barrier(0)
; template <class Epi, class Sched, bool ALIGN_EPI = false, bool SP2 = false, bool ABLK = false, bool BBLK = false>
; __device__ __forceinline__ void gemm_phase(PG8_LAS unsigned char* lds, const Gemm g, const Sched& S, const Epi& E) {
;     ...
;         for (int t = 0; t < nt; t += 2) {
;             const bool last = (t == nt - 2);
;             const char* a1 = cA + (size_t)(t + 1) * kstepA;
;             const char* a2 = last ? nA : cA + (size_t)(t + 2) * kstepA; const char* b2 = last ? nB : cB + (size_t)(t + 2) * kstepB;
;     ...
;             PG8_LDA(At, 1, 1); PG8_STAGE(PG8_SB(1, 0), b3, voffB); PG8_STAGE(PG8_SB(1, 1), b3 + hstepB, voffB); PG8_STAGE(PG8_SA(1, 0), a3, voffA);
;             PG8_WAIT_V(8); PG8_WAIT_L(0); PG8_BAR; PG8_MMA(1, 0, At, B0); PG8_MMA(1, 1, At, B1); PG8_BAR; PG8_SCHED;
;     ...
;         if constexpr (ALIGN_EPI) { if (wr == 0) PG8_BAR; }
	s_add_u32 s26, s24, 0x8000
	s_addc_u32 s27, s25, 0
	s_add_i32 s68, s68, s29
	s_mov_b32 m0, s68
	ds_read_b128 v[186:189], v157 offset:49152
	ds_read_b128 v[190:193], v157 offset:50176
	ds_read_b128 v[194:197], v157 offset:51200
	ds_read_b128 v[198:201], v157 offset:52224
	ds_read_b128 v[202:205], v157 offset:53248
	ds_read_b128 v[206:209], v157 offset:54272
	ds_read_b128 v[210:213], v157 offset:55296
	ds_read_b128 v[214:217], v157 offset:56320
	global_load_lds_dwordx4 v140, s[26:27]
	s_add_i32 m0, s68, 0x2000
	s_add_u32 s24, s24, 0xc000
	s_addc_u32 s25, s25, 0
	global_load_lds_dwordx4 v136, s[26:27]
	s_add_i32 s26, s69, s29
	s_mov_b32 m0, s26
	s_nop 0
	global_load_lds_dwordx4 v140, s[24:25]
	s_add_i32 m0, s26, 0x2000
	s_nop 0
	global_load_lds_dwordx4 v136, s[24:25]
	s_mov_b32 m0, s37
	s_nop 0
	global_load_lds_dwordx4 v142, s[22:23]
	s_mov_b32 m0, s62
	s_nop 0
	global_load_lds_dwordx4 v138, s[22:23]
	s_waitcnt vmcnt(8)
	s_waitcnt lgkmcnt(0)
	v_mfma_f32_16x16x32_bf16 v[68:71], v[150:153], v[186:189], v[68:71]
	v_mfma_f32_16x16x32_bf16 v[64:67], v[162:165], v[186:189], v[64:67]
	v_mfma_f32_16x16x32_bf16 v[60:63], v[150:153], v[194:197], v[60:63]
	v_mfma_f32_16x16x32_bf16 v[52:55], v[162:165], v[194:197], v[52:55]
	v_mfma_f32_16x16x32_bf16 v[44:47], v[150:153], v[202:205], v[44:47]
	v_mfma_f32_16x16x32_bf16 v[32:35], v[162:165], v[202:205], v[32:35]
	s_barrier
	s_setprio 1
	v_mfma_f32_16x16x32_bf16 v[24:27], v[150:153], v[210:213], v[24:27]
	v_mfma_f32_16x16x32_bf16 v[16:19], v[162:165], v[210:213], v[16:19]
	v_mfma_f32_16x16x32_bf16 v[68:71], v[158:161], v[190:193], v[68:71]
	v_mfma_f32_16x16x32_bf16 v[64:67], v[166:169], v[190:193], v[64:67]
	v_mfma_f32_16x16x32_bf16 v[60:63], v[158:161], v[198:201], v[60:63]
	v_mfma_f32_16x16x32_bf16 v[52:55], v[166:169], v[198:201], v[52:55]
	v_mfma_f32_16x16x32_bf16 v[44:47], v[158:161], v[206:209], v[44:47]
	v_mfma_f32_16x16x32_bf16 v[32:35], v[166:169], v[206:209], v[32:35]
	v_mfma_f32_16x16x32_bf16 v[24:27], v[158:161], v[214:217], v[24:27]
	v_mfma_f32_16x16x32_bf16 v[16:19], v[166:169], v[214:217], v[16:19]
	s_setprio 0
	s_setprio 1
	v_mfma_f32_16x16x32_bf16 v[56:59], v[170:173], v[186:189], v[56:59]
	v_mfma_f32_16x16x32_bf16 v[48:51], v[178:181], v[186:189], v[48:51]
	v_mfma_f32_16x16x32_bf16 v[40:43], v[170:173], v[194:197], v[40:43]
	v_mfma_f32_16x16x32_bf16 v[28:31], v[178:181], v[194:197], v[28:31]
	v_mfma_f32_16x16x32_bf16 v[20:23], v[170:173], v[202:205], v[20:23]
	v_mfma_f32_16x16x32_bf16 v[12:15], v[178:181], v[202:205], v[12:15]
	v_mfma_f32_16x16x32_bf16 v[8:11], v[170:173], v[210:213], v[8:11]
	v_mfma_f32_16x16x32_bf16 v[4:7], v[178:181], v[210:213], v[4:7]
	v_mfma_f32_16x16x32_bf16 v[56:59], v[174:177], v[190:193], v[56:59]
	v_mfma_f32_16x16x32_bf16 v[48:51], v[182:185], v[190:193], v[48:51]
	v_mfma_f32_16x16x32_bf16 v[40:43], v[174:177], v[198:201], v[40:43]
	v_mfma_f32_16x16x32_bf16 v[28:31], v[182:185], v[198:201], v[28:31]
	v_mfma_f32_16x16x32_bf16 v[20:23], v[174:177], v[206:209], v[20:23]
	v_mfma_f32_16x16x32_bf16 v[12:15], v[182:185], v[206:209], v[12:15]
	v_mfma_f32_16x16x32_bf16 v[8:11], v[174:177], v[214:217], v[8:11]
	v_mfma_f32_16x16x32_bf16 v[4:7], v[182:185], v[214:217], v[4:7]
	s_setprio 0
	s_barrier
	s_add_i32 s13, s13, 2
	s_add_u32 s20, s20, 0x10000
	s_addc_u32 s21, s21, 0
	s_add_u32 s70, s70, 0x10000
	s_addc_u32 s71, s71, 0
	s_cmp_gt_u32 s13, 29
	s_cbranch_scc0 .LBB0_916
	s_and_b64 vcc, exec, s[6:7]
	s_cbranch_vccz .LBB0_919
	s_barrier

; #define PG8_STAGE(bufoff, gbase, voff) do { _Pragma("unroll") for (int _i = 0; _i < 2; ++_i) \
;         __builtin_amdgcn_global_load_lds((const unsigned*)((const char*)(gbase) + (voff)[_i]), (PG8_LAS unsigned*)(lds + (bufoff) + ldsw + _i * 8192), 16, 0, 0); } while (0)
; #define PG8_LDA(dst, b, h) do { _Pragma("unroll") for (int m = 0; m < 4; ++m) _Pragma("unroll") for (int k = 0; k < 2; ++k) dst[m][k] = *(const PG8_LAS bf16x8*)(lds + PG8_SA(b, h) + aoff + m * 2048 + k * 1024); } while (0)
; #define PG8_WAIT_V(n) asm volatile("s_waitcnt vmcnt(" #n ")" ::: "memory")
; #define PG8_WAIT_L(n) asm volatile("s_waitcnt lgkmcnt(" #n ")" ::: "memory")
; template <class Epi, class Sched, bool ALIGN_EPI = false, bool SP2 = false, bool ABLK = false, bool BBLK = false>
; __device__ __forceinline__ void gemm_phase(PG8_LAS unsigned char* lds, const Gemm g, const Sched& S, const Epi& E) {
;     ...
;         for (int t = 0; t < nt; t += 2) {
;             const bool last = (t == nt - 2);
;             const char* a1 = cA + (size_t)(t + 1) * kstepA;
;             const char* a2 = last ? nA : cA + (size_t)(t + 2) * kstepA; const char* b2 = last ? nB : cB + (size_t)(t + 2) * kstepB;
;             const char* a3 = a2 + kstepA; const char* b3 = b2 + kstepB;
;             if (last && has_next) S.a_ready(nxt);
;             if constexpr (SP2) {
;             PG8_LDB(B0, 0, 0); PG8_LDB(B1, 0, 1); PG8_SCHED; PG8_LDA(At, 0, 0); PG8_STAGE(PG8_SA(1, 1), a1 + hstepA, voffA);
;             PG8_WAIT_V(8); PG8_WAIT_L(0); PG8_BAR; PG8_MMA(0, 0, At, B0); PG8_MMA(0, 1, At, B1); PG8_BAR; PG8_SCHED;
;             PG8_LDA(At, 0, 1); PG8_STAGE(PG8_SB(0, 0), b2, voffB); PG8_STAGE(PG8_SB(0, 1), b2 + hstepB, voffB); PG8_STAGE(PG8_SA(0, 0), a2, voffA);
;             PG8_WAIT_V(8); PG8_WAIT_L(0); PG8_BAR; PG8_MMA(1, 0, At, B0); PG8_MMA(1, 1, At, B1); PG8_BAR; PG8_SCHED;
;             PG8_LDB(B0, 1, 0); PG8_LDB(B1, 1, 1); PG8_SCHED; PG8_LDA(At, 1, 0); PG8_STAGE(PG8_SA(0, 1), a2 + hstepA, voffA);
;             PG8_WAIT_V(8); PG8_WAIT_L(0); PG8_BAR; PG8_MMA(0, 0, At, B0); PG8_MMA(0, 1, At, B1); PG8_BAR; PG8_SCHED;
;             PG8_LDA(At, 1, 1); PG8_STAGE(PG8_SB(1, 0), b3, voffB); PG8_STAGE(PG8_SB(1, 1), b3 + hstepB, voffB); PG8_STAGE(PG8_SA(1, 0), a3, voffA);
;             PG8_WAIT_V(8); PG8_WAIT_L(0); PG8_BAR; PG8_MMA(1, 0, At, B0); PG8_MMA(1, 1, At, B1); PG8_BAR; PG8_SCHED;
.LBB0_2111:
	s_add_u32 s24, s22, 0x4000
	s_addc_u32 s25, s23, 0
	s_cmp_eq_u32 s13, 28
	s_cselect_b32 s28, s17, s24
	s_cselect_b32 s29, s12, s25
	s_cselect_b32 s26, s77, s82
	s_cselect_b32 s27, s11, vcc_lo
	s_add_u32 s24, s28, 0x8000
	s_addc_u32 s25, s29, 0
	s_add_i32 s68, 0, 0x10000
	v_add_u32_e32 v151, s68, v148
	s_add_i32 s88, 0, 0x14000
	ds_read_b128 v[36:39], v151
	ds_read_b128 v[152:155], v151 offset:1024
	ds_read_b128 v[156:159], v151 offset:2048
	ds_read_b128 v[160:163], v151 offset:3072
	v_add_u32_e32 v151, s88, v148
	ds_read_b128 v[164:167], v151
	ds_read_b128 v[168:171], v151 offset:1024
	ds_read_b128 v[172:175], v151 offset:2048
	ds_read_b128 v[176:179], v151 offset:3072
	s_add_i32 m0, s9, 0xc000
	ds_read_b128 v[180:183], v150
	ds_read_b128 v[184:187], v150 offset:1024
	ds_read_b128 v[188:191], v150 offset:2048
	ds_read_b128 v[192:195], v150 offset:3072
	ds_read_b128 v[196:199], v150 offset:4096
	ds_read_b128 v[200:203], v150 offset:5120
	ds_read_b128 v[204:207], v150 offset:6144
	ds_read_b128 v[208:211], v150 offset:7168
	global_load_lds_dwordx4 v144, s[22:23]
	s_add_i32 m0, s9, 0xe000
	s_nop 0
	global_load_lds_dwordx4 v146, s[22:23]
	s_waitcnt vmcnt(8)
	s_waitcnt lgkmcnt(0)
	v_mfma_f32_16x16x32_bf16 v[132:135], v[36:39], v[180:183], v[132:135]
	v_mfma_f32_16x16x32_bf16 v[128:131], v[156:159], v[180:183], v[128:131]
	v_mfma_f32_16x16x32_bf16 v[124:127], v[36:39], v[188:191], v[124:127]
	v_mfma_f32_16x16x32_bf16 v[120:123], v[156:159], v[188:191], v[120:123]
	v_mfma_f32_16x16x32_bf16 v[108:111], v[36:39], v[196:199], v[108:111]
	v_mfma_f32_16x16x32_bf16 v[104:107], v[156:159], v[196:199], v[104:107]
	s_barrier
	s_setprio 1
	v_mfma_f32_16x16x32_bf16 v[92:95], v[36:39], v[204:207], v[92:95]
	v_mfma_f32_16x16x32_bf16 v[88:91], v[156:159], v[204:207], v[88:91]
	v_mfma_f32_16x16x32_bf16 v[132:135], v[152:155], v[184:187], v[132:135]
	v_mfma_f32_16x16x32_bf16 v[128:131], v[160:163], v[184:187], v[128:131]
	v_mfma_f32_16x16x32_bf16 v[124:127], v[152:155], v[192:195], v[124:127]
	v_mfma_f32_16x16x32_bf16 v[120:123], v[160:163], v[192:195], v[120:123]
	v_mfma_f32_16x16x32_bf16 v[108:111], v[152:155], v[200:203], v[108:111]
	v_mfma_f32_16x16x32_bf16 v[104:107], v[160:163], v[200:203], v[104:107]
	v_mfma_f32_16x16x32_bf16 v[92:95], v[152:155], v[208:211], v[92:95]
	v_mfma_f32_16x16x32_bf16 v[88:91], v[160:163], v[208:211], v[88:91]
	s_setprio 0
	s_setprio 1
	v_mfma_f32_16x16x32_bf16 v[116:119], v[164:167], v[180:183], v[116:119]
	v_mfma_f32_16x16x32_bf16 v[112:115], v[172:175], v[180:183], v[112:115]
	v_mfma_f32_16x16x32_bf16 v[100:103], v[164:167], v[188:191], v[100:103]
	v_mfma_f32_16x16x32_bf16 v[96:99], v[172:175], v[188:191], v[96:99]
	v_mfma_f32_16x16x32_bf16 v[84:87], v[164:167], v[196:199], v[84:87]
	v_mfma_f32_16x16x32_bf16 v[80:83], v[172:175], v[196:199], v[80:83]
	v_mfma_f32_16x16x32_bf16 v[76:79], v[164:167], v[204:207], v[76:79]
	v_mfma_f32_16x16x32_bf16 v[72:75], v[172:175], v[204:207], v[72:75]
	v_mfma_f32_16x16x32_bf16 v[116:119], v[168:171], v[184:187], v[116:119]
	v_mfma_f32_16x16x32_bf16 v[112:115], v[176:179], v[184:187], v[112:115]
	v_mfma_f32_16x16x32_bf16 v[100:103], v[168:171], v[192:195], v[100:103]
	v_mfma_f32_16x16x32_bf16 v[96:99], v[176:179], v[192:195], v[96:99]
	v_mfma_f32_16x16x32_bf16 v[84:87], v[168:171], v[200:203], v[84:87]
	v_mfma_f32_16x16x32_bf16 v[80:83], v[176:179], v[200:203], v[80:83]
	v_mfma_f32_16x16x32_bf16 v[76:79], v[168:171], v[208:211], v[76:79]
	v_mfma_f32_16x16x32_bf16 v[72:75], v[176:179], v[208:211], v[72:75]
	s_setprio 0
	s_barrier
	s_add_i32 s68, s68, s34
	s_mov_b32 m0, s68
	ds_read_b128 v[180:183], v150 offset:16384
	ds_read_b128 v[184:187], v150 offset:17408
	ds_read_b128 v[188:191], v150 offset:18432
	ds_read_b128 v[192:195], v150 offset:19456
	ds_read_b128 v[196:199], v150 offset:20480
	ds_read_b128 v[200:203], v150 offset:21504
	ds_read_b128 v[204:207], v150 offset:22528
	ds_read_b128 v[208:211], v150 offset:23552
	global_load_lds_dwordx4 v138, s[26:27]
	s_add_i32 m0, s68, 0x2000
	s_add_u32 s68, s26, 0x4000
	s_addc_u32 s69, s27, 0
	s_add_i32 s88, s88, s34
	global_load_lds_dwordx4 v142, s[26:27]
	s_mov_b32 m0, s88
	s_nop 0
	global_load_lds_dwordx4 v138, s[68:69]
	s_add_i32 m0, s88, 0x2000
	s_nop 0
	global_load_lds_dwordx4 v142, s[68:69]
	s_mov_b32 m0, s9
	s_nop 0
	global_load_lds_dwordx4 v136, s[28:29]
	s_mov_b32 m0, s35
	s_nop 0
	global_load_lds_dwordx4 v140, s[28:29]
	s_waitcnt vmcnt(8)
	s_waitcnt lgkmcnt(0)
	v_mfma_f32_16x16x32_bf16 v[68:71], v[36:39], v[180:183], v[68:71]
	v_mfma_f32_16x16x32_bf16 v[64:67], v[156:159], v[180:183], v[64:67]
	v_mfma_f32_16x16x32_bf16 v[60:63], v[36:39], v[188:191], v[60:63]
	v_mfma_f32_16x16x32_bf16 v[56:59], v[156:159], v[188:191], v[56:59]
	v_mfma_f32_16x16x32_bf16 v[44:47], v[36:39], v[196:199], v[44:47]
	v_mfma_f32_16x16x32_bf16 v[40:43], v[156:159], v[196:199], v[40:43]
	s_barrier
; #define PG8_STAGE(bufoff, gbase, voff) do { _Pragma("unroll") for (int _i = 0; _i < 2; ++_i) \
;         __builtin_amdgcn_global_load_lds((const unsigned*)((const char*)(gbase) + (voff)[_i]), (PG8_LAS unsigned*)(lds + (bufoff) + ldsw + _i * 8192), 16, 0, 0); } while (0)
; #define PG8_LDA(dst, b, h) do { _Pragma("unroll") for (int m = 0; m < 4; ++m) _Pragma("unroll") for (int k = 0; k < 2; ++k) dst[m][k] = *(const PG8_LAS bf16x8*)(lds + PG8_SA(b, h) + aoff + m * 2048 + k * 1024); } while (0)
; #define PG8_LDB(dst, b, h) do { _Pragma("unroll") for (int n = 0; n < 2; ++n) _Pragma("unroll") for (int k = 0; k < 2; ++k) dst[n][k] = *(const PG8_LAS bf16x8*)(lds + PG8_SB(b, h) + boff + n * 2048 + k * 1024); } while (0)
; #define PG8_MMA(ai, bj, At, Bt) do { __builtin_amdgcn_s_setprio(1); _Pragma("unroll") for (int m = 0; m < 4; ++m) _Pragma("unroll") for (int n = 0; n < 2; ++n) _Pragma("unroll") for (int k = 0; k < 2; ++k) \
;         acc[ai][bj][m][n] = __builtin_amdgcn_mfma_f32_16x16x32_bf16(Bt[n][k], At[m][k], acc[ai][bj][m][n], 0, 0, 0); __builtin_amdgcn_s_setprio(0); } while (0)
; template <class Epi, class Sched, bool ALIGN_EPI = false, bool SP2 = false, bool ABLK = false, bool BBLK = false>
; __device__ __forceinline__ void gemm_phase(PG8_LAS unsigned char* lds, const Gemm g, const Sched& S, const Epi& E) {
;     ...
;             PG8_LDB(B0, 0, 0); PG8_LDB(B1, 0, 1); PG8_SCHED; PG8_LDA(At, 0, 0); PG8_STAGE(PG8_SA(1, 1), a1 + hstepA, voffA);
;             PG8_WAIT_V(8); PG8_WAIT_L(0); PG8_BAR; PG8_MMA(0, 0, At, B0); PG8_MMA(0, 1, At, B1); PG8_BAR; PG8_SCHED;
;             PG8_LDA(At, 0, 1); PG8_STAGE(PG8_SB(0, 0), b2, voffB); PG8_STAGE(PG8_SB(0, 1), b2 + hstepB, voffB); PG8_STAGE(PG8_SA(0, 0), a2, voffA);
;             PG8_WAIT_V(8); PG8_WAIT_L(0); PG8_BAR; PG8_MMA(1, 0, At, B0); PG8_MMA(1, 1, At, B1); PG8_BAR; PG8_SCHED;
;             PG8_LDB(B0, 1, 0); PG8_LDB(B1, 1, 1); PG8_SCHED; PG8_LDA(At, 1, 0); PG8_STAGE(PG8_SA(0, 1), a2 + hstepA, voffA);
;             PG8_WAIT_V(8); PG8_WAIT_L(0); PG8_BAR; PG8_MMA(0, 0, At, B0); PG8_MMA(0, 1, At, B1); PG8_BAR; PG8_SCHED;
;             PG8_LDA(At, 1, 1); PG8_STAGE(PG8_SB(1, 0), b3, voffB); PG8_STAGE(PG8_SB(1, 1), b3 + hstepB, voffB); PG8_STAGE(PG8_SA(1, 0), a3, voffA);
;             PG8_WAIT_V(8); PG8_WAIT_L(0); PG8_BAR; PG8_MMA(1, 0, At, B0); PG8_MMA(1, 1, At, B1); PG8_BAR; PG8_SCHED;
	s_setprio 1
	v_mfma_f32_16x16x32_bf16 v[24:27], v[36:39], v[204:207], v[24:27]
	v_mfma_f32_16x16x32_bf16 v[20:23], v[156:159], v[204:207], v[20:23]
	v_mfma_f32_16x16x32_bf16 v[68:71], v[152:155], v[184:187], v[68:71]
	v_mfma_f32_16x16x32_bf16 v[64:67], v[160:163], v[184:187], v[64:67]
	v_mfma_f32_16x16x32_bf16 v[60:63], v[152:155], v[192:195], v[60:63]
	v_mfma_f32_16x16x32_bf16 v[56:59], v[160:163], v[192:195], v[56:59]
	v_mfma_f32_16x16x32_bf16 v[44:47], v[152:155], v[200:203], v[44:47]
	v_mfma_f32_16x16x32_bf16 v[40:43], v[160:163], v[200:203], v[40:43]
	v_mfma_f32_16x16x32_bf16 v[24:27], v[152:155], v[208:211], v[24:27]
	v_mfma_f32_16x16x32_bf16 v[20:23], v[160:163], v[208:211], v[20:23]
	s_setprio 0
	s_setprio 1
	v_mfma_f32_16x16x32_bf16 v[48:51], v[172:175], v[180:183], v[48:51]
	v_mfma_f32_16x16x32_bf16 v[32:35], v[164:167], v[188:191], v[32:35]
	v_mfma_f32_16x16x32_bf16 v[28:31], v[172:175], v[188:191], v[28:31]
	v_mfma_f32_16x16x32_bf16 v[16:19], v[164:167], v[196:199], v[16:19]
	v_mfma_f32_16x16x32_bf16 v[12:15], v[172:175], v[196:199], v[12:15]
	v_mfma_f32_16x16x32_bf16 v[8:11], v[164:167], v[204:207], v[8:11]
	v_mfma_f32_16x16x32_bf16 v[4:7], v[172:175], v[204:207], v[4:7]
	v_mfma_f32_16x16x32_bf16 v[36:39], v[164:167], v[180:183], v[52:55]
	v_mfma_f32_16x16x32_bf16 v[48:51], v[176:179], v[184:187], v[48:51]
	v_mfma_f32_16x16x32_bf16 v[32:35], v[168:171], v[192:195], v[32:35]
	v_mfma_f32_16x16x32_bf16 v[28:31], v[176:179], v[192:195], v[28:31]
	v_mfma_f32_16x16x32_bf16 v[16:19], v[168:171], v[200:203], v[16:19]
	v_mfma_f32_16x16x32_bf16 v[12:15], v[176:179], v[200:203], v[12:15]
	v_mfma_f32_16x16x32_bf16 v[8:11], v[168:171], v[208:211], v[8:11]
	v_mfma_f32_16x16x32_bf16 v[4:7], v[176:179], v[208:211], v[4:7]
	v_mfma_f32_16x16x32_bf16 v[36:39], v[168:171], v[184:187], v[36:39]
	s_setprio 0
	s_barrier
	s_add_i32 s68, 0, 0x18000
	v_add_u32_e32 v151, s68, v148
	s_add_i32 s69, 0, 0x1c000
	ds_read_b128 v[52:55], v151
	ds_read_b128 v[152:155], v151 offset:1024
	ds_read_b128 v[156:159], v151 offset:2048
	ds_read_b128 v[160:163], v151 offset:3072
	v_add_u32_e32 v151, s69, v148
	ds_read_b128 v[164:167], v151
	ds_read_b128 v[168:171], v151 offset:1024
	ds_read_b128 v[172:175], v151 offset:2048
	ds_read_b128 v[176:179], v151 offset:3072
	s_add_u32 s28, s28, 0x4000
	s_addc_u32 s29, s29, 0
	s_mov_b32 m0, s36
	ds_read_b128 v[180:183], v150 offset:32768
	ds_read_b128 v[184:187], v150 offset:33792
	ds_read_b128 v[188:191], v150 offset:34816
	ds_read_b128 v[192:195], v150 offset:35840
	ds_read_b128 v[196:199], v150 offset:36864
	ds_read_b128 v[200:203], v150 offset:37888
	ds_read_b128 v[204:207], v150 offset:38912
	ds_read_b128 v[208:211], v150 offset:39936
	global_load_lds_dwordx4 v136, s[28:29]
	s_mov_b32 m0, s37
	s_nop 0
	global_load_lds_dwordx4 v140, s[28:29]
	s_waitcnt vmcnt(8)
	s_waitcnt lgkmcnt(0)
	v_mfma_f32_16x16x32_bf16 v[132:135], v[52:55], v[180:183], v[132:135]
	v_mfma_f32_16x16x32_bf16 v[128:131], v[156:159], v[180:183], v[128:131]
	v_mfma_f32_16x16x32_bf16 v[124:127], v[52:55], v[188:191], v[124:127]
	v_mfma_f32_16x16x32_bf16 v[120:123], v[156:159], v[188:191], v[120:123]
	v_mfma_f32_16x16x32_bf16 v[108:111], v[52:55], v[196:199], v[108:111]
	v_mfma_f32_16x16x32_bf16 v[104:107], v[156:159], v[196:199], v[104:107]
	s_barrier
	s_setprio 1
	v_mfma_f32_16x16x32_bf16 v[92:95], v[52:55], v[204:207], v[92:95]
	v_mfma_f32_16x16x32_bf16 v[88:91], v[156:159], v[204:207], v[88:91]
	v_mfma_f32_16x16x32_bf16 v[132:135], v[152:155], v[184:187], v[132:135]
	v_mfma_f32_16x16x32_bf16 v[128:131], v[160:163], v[184:187], v[128:131]
	v_mfma_f32_16x16x32_bf16 v[124:127], v[152:155], v[192:195], v[124:127]
	v_mfma_f32_16x16x32_bf16 v[120:123], v[160:163], v[192:195], v[120:123]
	v_mfma_f32_16x16x32_bf16 v[108:111], v[152:155], v[200:203], v[108:111]
	v_mfma_f32_16x16x32_bf16 v[104:107], v[160:163], v[200:203], v[104:107]
	v_mfma_f32_16x16x32_bf16 v[92:95], v[152:155], v[208:211], v[92:95]
	v_mfma_f32_16x16x32_bf16 v[88:91], v[160:163], v[208:211], v[88:91]
	s_setprio 0
	s_setprio 1
	v_mfma_f32_16x16x32_bf16 v[116:119], v[164:167], v[180:183], v[116:119]
	v_mfma_f32_16x16x32_bf16 v[112:115], v[172:175], v[180:183], v[112:115]
	v_mfma_f32_16x16x32_bf16 v[100:103], v[164:167], v[188:191], v[100:103]
	v_mfma_f32_16x16x32_bf16 v[96:99], v[172:175], v[188:191], v[96:99]
	v_mfma_f32_16x16x32_bf16 v[84:87], v[164:167], v[196:199], v[84:87]
	v_mfma_f32_16x16x32_bf16 v[80:83], v[172:175], v[196:199], v[80:83]
	v_mfma_f32_16x16x32_bf16 v[76:79], v[164:167], v[204:207], v[76:79]
	v_mfma_f32_16x16x32_bf16 v[72:75], v[172:175], v[204:207], v[72:75]
	v_mfma_f32_16x16x32_bf16 v[116:119], v[168:171], v[184:187], v[116:119]
	v_mfma_f32_16x16x32_bf16 v[112:115], v[176:179], v[184:187], v[112:115]
	v_mfma_f32_16x16x32_bf16 v[100:103], v[168:171], v[192:195], v[100:103]
	v_mfma_f32_16x16x32_bf16 v[96:99], v[176:179], v[192:195], v[96:99]
	v_mfma_f32_16x16x32_bf16 v[84:87], v[168:171], v[200:203], v[84:87]
	v_mfma_f32_16x16x32_bf16 v[80:83], v[176:179], v[200:203], v[80:83]
	v_mfma_f32_16x16x32_bf16 v[76:79], v[168:171], v[208:211], v[76:79]
	v_mfma_f32_16x16x32_bf16 v[72:75], v[176:179], v[208:211], v[72:75]
	s_setprio 0
	s_barrier
; #define PG8_STAGE(bufoff, gbase, voff) do { _Pragma("unroll") for (int _i = 0; _i < 2; ++_i) \
;         __builtin_amdgcn_global_load_lds((const unsigned*)((const char*)(gbase) + (voff)[_i]), (PG8_LAS unsigned*)(lds + (bufoff) + ldsw + _i * 8192), 16, 0, 0); } while (0)
; #define PG8_LDA(dst, b, h) do { _Pragma("unroll") for (int m = 0; m < 4; ++m) _Pragma("unroll") for (int k = 0; k < 2; ++k) dst[m][k] = *(const PG8_LAS bf16x8*)(lds + PG8_SA(b, h) + aoff + m * 2048 + k * 1024); } while (0)
; #define PG8_MMA(ai, bj, At, Bt) do { __builtin_amdgcn_s_setprio(1); _Pragma("unroll") for (int m = 0; m < 4; ++m) _Pragma("unroll") for (int n = 0; n < 2; ++n) _Pragma("unroll") for (int k = 0; k < 2; ++k) \
;         acc[ai][bj][m][n] = __builtin_amdgcn_mfma_f32_16x16x32_bf16(Bt[n][k], At[m][k], acc[ai][bj][m][n], 0, 0, 0); __builtin_amdgcn_s_setprio(0); } while (0)
; #define PG8_WAIT_V(n) asm volatile("s_waitcnt vmcnt(" #n ")" ::: "memory")
; #define PG8_WAIT_L(n) asm volatile("s_waitcnt lgkmcnt(" #n ")" ::: "memory")
; #define PG8_BAR __builtin_amdgcn_s_barrier()
; #define PG8_SCHED __builtin_amdgcn_sched_barrier(0)
; template <class Epi, class Sched, bool ALIGN_EPI = false, bool SP2 = false, bool ABLK = false, bool BBLK = false>
; __device__ __forceinline__ void gemm_phase(PG8_LAS unsigned char* lds, const Gemm g, const Sched& S, const Epi& E) {
;     ...
;         for (int t = 0; t < nt; t += 2) {
;             const bool last = (t == nt - 2);
;             const char* a1 = cA + (size_t)(t + 1) * kstepA;
;             const char* a2 = last ? nA : cA + (size_t)(t + 2) * kstepA; const char* b2 = last ? nB : cB + (size_t)(t + 2) * kstepB;
;     ...
;             PG8_LDA(At, 1, 1); PG8_STAGE(PG8_SB(1, 0), b3, voffB); PG8_STAGE(PG8_SB(1, 1), b3 + hstepB, voffB); PG8_STAGE(PG8_SA(1, 0), a3, voffA);
;             PG8_WAIT_V(8); PG8_WAIT_L(0); PG8_BAR; PG8_MMA(1, 0, At, B0); PG8_MMA(1, 1, At, B1); PG8_BAR; PG8_SCHED;
;     ...
;         if constexpr (ALIGN_EPI) { if (wr == 0) PG8_BAR; }
	s_add_u32 s28, s26, 0x8000
	s_addc_u32 s29, s27, 0
	s_add_i32 s68, s68, s34
	s_mov_b32 m0, s68
	ds_read_b128 v[180:183], v150 offset:49152
	ds_read_b128 v[184:187], v150 offset:50176
	ds_read_b128 v[188:191], v150 offset:51200
	ds_read_b128 v[192:195], v150 offset:52224
	ds_read_b128 v[196:199], v150 offset:53248
	ds_read_b128 v[200:203], v150 offset:54272
	ds_read_b128 v[204:207], v150 offset:55296
	ds_read_b128 v[208:211], v150 offset:56320
	global_load_lds_dwordx4 v138, s[28:29]
	s_add_i32 m0, s68, 0x2000
	s_add_u32 s26, s26, 0xc000
	s_addc_u32 s27, s27, 0
	global_load_lds_dwordx4 v142, s[28:29]
	s_add_i32 s28, s69, s34
	s_mov_b32 m0, s28
	s_nop 0
	global_load_lds_dwordx4 v138, s[26:27]
	s_add_i32 m0, s28, 0x2000
	s_nop 0
	global_load_lds_dwordx4 v142, s[26:27]
	s_mov_b32 m0, s64
	s_nop 0
	global_load_lds_dwordx4 v136, s[24:25]
	s_mov_b32 m0, s65
	s_nop 0
	global_load_lds_dwordx4 v140, s[24:25]
	s_waitcnt vmcnt(8)
	s_waitcnt lgkmcnt(0)
	v_mfma_f32_16x16x32_bf16 v[68:71], v[52:55], v[180:183], v[68:71]
	v_mfma_f32_16x16x32_bf16 v[64:67], v[156:159], v[180:183], v[64:67]
	v_mfma_f32_16x16x32_bf16 v[60:63], v[52:55], v[188:191], v[60:63]
	v_mfma_f32_16x16x32_bf16 v[56:59], v[156:159], v[188:191], v[56:59]
	v_mfma_f32_16x16x32_bf16 v[44:47], v[52:55], v[196:199], v[44:47]
	v_mfma_f32_16x16x32_bf16 v[40:43], v[156:159], v[196:199], v[40:43]
	s_barrier
	s_setprio 1
	v_mfma_f32_16x16x32_bf16 v[24:27], v[52:55], v[204:207], v[24:27]
	v_mfma_f32_16x16x32_bf16 v[20:23], v[156:159], v[204:207], v[20:23]
	v_mfma_f32_16x16x32_bf16 v[68:71], v[152:155], v[184:187], v[68:71]
	v_mfma_f32_16x16x32_bf16 v[64:67], v[160:163], v[184:187], v[64:67]
	v_mfma_f32_16x16x32_bf16 v[60:63], v[152:155], v[192:195], v[60:63]
	v_mfma_f32_16x16x32_bf16 v[56:59], v[160:163], v[192:195], v[56:59]
	v_mfma_f32_16x16x32_bf16 v[44:47], v[152:155], v[200:203], v[44:47]
	v_mfma_f32_16x16x32_bf16 v[40:43], v[160:163], v[200:203], v[40:43]
	v_mfma_f32_16x16x32_bf16 v[24:27], v[152:155], v[208:211], v[24:27]
	v_mfma_f32_16x16x32_bf16 v[20:23], v[160:163], v[208:211], v[20:23]
	s_setprio 0
	s_setprio 1
	v_mfma_f32_16x16x32_bf16 v[36:39], v[164:167], v[180:183], v[36:39]
	v_mfma_f32_16x16x32_bf16 v[52:55], v[168:171], v[184:187], v[36:39]
	v_mfma_f32_16x16x32_bf16 v[36:39], v[172:175], v[180:183], v[48:51]
	v_mfma_f32_16x16x32_bf16 v[32:35], v[164:167], v[188:191], v[32:35]
	v_mfma_f32_16x16x32_bf16 v[28:31], v[172:175], v[188:191], v[28:31]
	v_mfma_f32_16x16x32_bf16 v[16:19], v[164:167], v[196:199], v[16:19]
	v_mfma_f32_16x16x32_bf16 v[12:15], v[172:175], v[196:199], v[12:15]
	v_mfma_f32_16x16x32_bf16 v[8:11], v[164:167], v[204:207], v[8:11]
	v_mfma_f32_16x16x32_bf16 v[4:7], v[172:175], v[204:207], v[4:7]
	v_mfma_f32_16x16x32_bf16 v[48:51], v[176:179], v[184:187], v[36:39]
	v_mfma_f32_16x16x32_bf16 v[32:35], v[168:171], v[192:195], v[32:35]
	v_mfma_f32_16x16x32_bf16 v[28:31], v[176:179], v[192:195], v[28:31]
	v_mfma_f32_16x16x32_bf16 v[16:19], v[168:171], v[200:203], v[16:19]
	v_mfma_f32_16x16x32_bf16 v[12:15], v[176:179], v[200:203], v[12:15]
	v_mfma_f32_16x16x32_bf16 v[8:11], v[168:171], v[208:211], v[8:11]
	v_mfma_f32_16x16x32_bf16 v[4:7], v[176:179], v[208:211], v[4:7]
	s_setprio 0
	s_barrier
	s_add_i32 s13, s13, 2
	s_add_u32 s22, s22, 0x10000
	s_addc_u32 s23, s23, 0
	s_add_u32 s82, s82, 0x10000
	s_addc_u32 vcc_lo, vcc_lo, 0
	s_cmp_gt_u32 s13, 29
	s_cbranch_scc0 .LBB0_2111
	s_and_b64 vcc, exec, s[6:7]
	s_movk_i32 s77, 0x1000
	s_cbranch_vccz .LBB0_2114
	s_barrier
